# aggreg: chunk aggregates reduced in registers inside the P2b gates epilogue (DPP lane scan + LDS hand-off between the two row halves); P2c phase and its grid barrier removed
# speedup vs baseline: 1.0065x; 1.0065x over previous
; __device__ __forceinline__ unsigned cvt_pk_bf16(float lo, float hi) { unsigned r; asm volatile("v_cvt_pk_bf16_f32 %0, %1, %2" : "=v"(r) : "v"(lo), "v"(hi)); return r; }
; __device__ __forceinline__ float bf_lo(unsigned w) { return __uint_as_float(w << 16); }
; __device__ __forceinline__ float bf_hi(unsigned w) { return __uint_as_float(w & 0xffff0000u); }
;     __device__ __forceinline__ void operator()(EPI_ARGS) const {
;         const int c0 = (u.pn >> 1) * 256 + (u.pn & 1) * 128 + wc * 32 + 8 * fq;
;         u32x4 vv[2][4];
; #pragma unroll
;         for (int ai = 0; ai < 2; ++ai)
; #pragma unroll
;             for (int m = 0; m < 4; ++m) vv[ai][m] = *(const u32x4*)(V + (size_t)ROW_OF(ai, m) * LW + c0);
;         f32x4 ba[2], bi[2], sp[2];
; #pragma unroll
;         for (int n = 0; n < 2; ++n) { ba[n] = *(const f32x4*)(b_a + c0 + 4 * n); bi[n] = *(const f32x4*)(b_i + c0 + 4 * n); sp[n] = *(const f32x4*)(sp8 + c0 + 4 * n); }
; #pragma unroll
;         for (int ai = 0; ai < 2; ++ai)
; #pragma unroll
;             for (int m = 0; m < 4; ++m) {
;                 const int row = ROW_OF(ai, m);
; #pragma unroll
;                 for (int n = 0; n < 2; ++n) {
;                     const unsigned w0 = n ? vv[ai][m].z : vv[ai][m].x, w1 = n ? vv[ai][m].w : vv[ai][m].y;
;                     const f32x4 vx = (f32x4){bf_lo(w0), bf_hi(w0), bf_lo(w1), bf_hi(w1)};
;                     const f32x4 r = sigmoid4(acc[ai][0][m][n] + ba[n]), ig = sigmoid4(acc[ai][1][m][n] + bi[n]);
;                     const f32x4 la = sp[n] * r * (-1.4426950409f);
;                     f32x4 av;
; #pragma unroll
;                     for (int j = 0; j < 4; ++j) av[j] = __builtin_amdgcn_exp2f(la[j]);
;                     const f32x4 om = 1.0f - av * av; f32x4 sq;
; #pragma unroll
;                     for (int j = 0; j < 4; ++j) sq[j] = __builtin_amdgcn_sqrtf(om[j]);
;                     const f32x4 bx = sq * ig * vx;
;                     u32x4 w; w.x = cvt_pk_bf16(la[0], bx[0]); w.y = cvt_pk_bf16(la[1], bx[1]); w.z = cvt_pk_bf16(la[2], bx[2]); w.w = cvt_pk_bf16(la[3], bx[3]);
;                     *(u32x4*)(AB + (size_t)row * LW + c0 + 4 * n) = w;
;                 }
;             }
.LBB0_556:
	v_mov_b32_e32 v65, v215
	v_mov_b32_e32 v64, v216
	s_lshl_b32 s0, s27, 7
	s_or_b32 s0, s0, s21
	v_lshl_add_u32 v64, v64, 3, s0
	s_lshl_b32 s0, s74, 8
	s_add_i32 s0, s0, s19
	v_add_u32_e32 v68, s0, v65
	v_ashrrev_i32_e32 v65, 31, v64
	v_ashrrev_i32_e32 v69, 31, v68
	v_lshl_add_u64 v[70:71], v[64:65], 1, s[54:55]
	v_lshlrev_b64 v[66:67], 12, v[68:69]
	v_lshlrev_b64 v[196:197], 2, v[64:65]
	v_lshl_add_u64 v[66:67], v[70:71], 0, v[66:67]
	v_lshl_add_u64 v[64:65], s[38:39], 0, v[196:197]
	global_load_dwordx4 v[180:183], v[66:67], off
	global_load_dwordx4 v[100:103], v[64:65], off
	v_lshl_add_u64 v[66:67], s[42:43], 0, v[196:197]
	global_load_dwordx4 v[92:95], v[66:67], off
	v_lshl_add_u64 v[108:109], s[56:57], 0, v[196:197]
	global_load_dwordx4 v[88:91], v[108:109], off
	global_load_dwordx4 v[80:83], v[64:65], off offset:16
	global_load_dwordx4 v[72:75], v[66:67], off offset:16
	s_nop 0
	global_load_dwordx4 v[64:67], v[108:109], off offset:16
	v_add_u32_e32 v210, 16, v68
	v_add_u32_e32 v208, 32, v68
	v_add_u32_e32 v206, 48, v68
	v_add_u32_e32 v204, 0x80, v68
	v_add_u32_e32 v202, 0x90, v68
	v_add_u32_e32 v200, 0xa0, v68
	v_add_u32_e32 v198, 0xb0, v68
	v_ashrrev_i32_e32 v211, 31, v210
	v_ashrrev_i32_e32 v209, 31, v208
	v_ashrrev_i32_e32 v207, 31, v206
	v_ashrrev_i32_e32 v205, 31, v204
	v_ashrrev_i32_e32 v203, 31, v202
	v_ashrrev_i32_e32 v201, 31, v200
	v_ashrrev_i32_e32 v199, 31, v198
	v_lshlrev_b64 v[222:223], 13, v[68:69]
	v_lshlrev_b64 v[68:69], 12, v[210:211]
	v_lshlrev_b64 v[108:109], 12, v[208:209]
	v_lshlrev_b64 v[110:111], 12, v[206:207]
	v_lshlrev_b64 v[128:129], 12, v[204:205]
	v_lshlrev_b64 v[130:131], 12, v[202:203]
	v_lshlrev_b64 v[148:149], 12, v[200:201]
	v_lshlrev_b64 v[150:151], 12, v[198:199]
	v_lshl_add_u64 v[68:69], v[70:71], 0, v[68:69]
	v_lshl_add_u64 v[108:109], v[70:71], 0, v[108:109]
	v_lshl_add_u64 v[110:111], v[70:71], 0, v[110:111]
	v_lshl_add_u64 v[128:129], v[70:71], 0, v[128:129]
	v_lshl_add_u64 v[130:131], v[70:71], 0, v[130:131]
	v_lshl_add_u64 v[224:225], v[70:71], 0, v[148:149]
	v_lshl_add_u64 v[70:71], v[70:71], 0, v[150:151]
	global_load_dwordx4 v[176:179], v[68:69], off
	global_load_dwordx4 v[172:175], v[108:109], off
	global_load_dwordx4 v[164:167], v[110:111], off
	global_load_dwordx4 v[148:151], v[128:129], off
	s_nop 0
	global_load_dwordx4 v[128:131], v[130:131], off
	s_nop 0
	global_load_dwordx4 v[108:111], v[224:225], off
	s_nop 0
	global_load_dwordx4 v[68:71], v[70:71], off
	v_readlane_b32 s80, v248, 11
	v_readlane_b32 s92, v248, 23
	v_readlane_b32 s93, v248, 24
	v_readlane_b32 s81, v248, 12
	v_readlane_b32 s82, v248, 13
	v_readlane_b32 s83, v248, 14
	v_readlane_b32 s84, v248, 15
	v_readlane_b32 s85, v248, 16
	v_readlane_b32 s86, v248, 17
	v_readlane_b32 s87, v248, 18
	v_readlane_b32 s88, v248, 19
	v_readlane_b32 s89, v248, 20
	v_readlane_b32 s90, v248, 21
	v_readlane_b32 s91, v248, 22
	v_readlane_b32 s94, v248, 25
	v_readlane_b32 s95, v248, 26
	s_and_b64 vcc, exec, s[4:5]
	s_mov_b64 s[0:1], -1
	s_waitcnt vmcnt(0)
	v_lshlrev_b32_e32 v224, 16, v180
	v_pk_add_f32 v[168:169], v[168:169], v[100:101]
	v_pk_add_f32 v[170:171], v[170:171], v[102:103]
	v_pk_add_f32 v[160:161], v[160:161], v[92:93]
	v_mul_f32_e32 v168, 0xbfb8aa3b, v168
	v_mul_f32_e32 v169, 0xbfb8aa3b, v169
	v_mul_f32_e32 v170, 0xbfb8aa3b, v170
	v_mul_f32_e32 v171, 0xbfb8aa3b, v171
	v_mul_f32_e32 v160, 0xbfb8aa3b, v160
	v_mul_f32_e32 v161, 0xbfb8aa3b, v161
	v_exp_f32_e32 v168, v168
	v_exp_f32_e32 v169, v169
	v_pk_add_f32 v[162:163], v[162:163], v[94:95]
	v_exp_f32_e32 v170, v170
	v_exp_f32_e32 v171, v171
	v_exp_f32_e32 v160, v160
	v_exp_f32_e32 v161, v161
	v_mul_f32_e32 v162, 0xbfb8aa3b, v162
	v_mul_f32_e32 v163, 0xbfb8aa3b, v163
	v_exp_f32_e32 v162, v162
	v_and_b32_e32 v225, 0xffff0000, v180
	v_exp_f32_e32 v180, v163
	v_add_f32_e32 v163, 1.0, v168
	v_add_f32_e32 v168, 1.0, v169
	v_add_f32_e32 v169, 1.0, v170
	v_add_f32_e32 v170, 1.0, v171
	v_add_f32_e32 v171, 1.0, v160
	v_add_f32_e32 v221, 1.0, v161
	v_rcp_f32_e32 v160, v163
	v_rcp_f32_e32 v161, v168
	v_add_f32_e32 v226, 1.0, v162
	v_rcp_f32_e32 v162, v169
	v_rcp_f32_e32 v163, v170
	v_pk_mul_f32 v[160:161], v[88:89], v[160:161]
	v_rcp_f32_e32 v170, v226
	v_pk_mul_f32 v[160:161], v[160:161], s[62:63] op_sel_hi:[1,0]
	v_pk_mul_f32 v[162:163], v[90:91], v[162:163]
	v_exp_f32_e32 v226, v160
	v_exp_f32_e32 v227, v161
	v_pk_mul_f32 v[162:163], v[162:163], s[62:63] op_sel_hi:[1,0]
	v_pk_add_f32 v[156:157], v[156:157], v[80:81]
	v_exp_f32_e32 v228, v162
	v_exp_f32_e32 v229, v163
	v_pk_add_f32 v[158:159], v[158:159], v[82:83]
	v_mul_f32_e32 v156, 0xbfb8aa3b, v156
	v_mul_f32_e32 v157, 0xbfb8aa3b, v157
	v_pk_mul_f32 v[226:227], v[226:227], v[226:227]
	v_exp_f32_e32 v156, v156
	v_exp_f32_e32 v157, v157
	v_mul_f32_e32 v158, 0xbfb8aa3b, v158
	v_mul_f32_e32 v159, 0xbfb8aa3b, v159
	v_rcp_f32_e32 v168, v171
	v_add_f32_e32 v171, 1.0, v180
	v_sub_f32_e32 v180, 1.0, v226
	v_exp_f32_e32 v158, v158
	v_exp_f32_e32 v159, v159
	v_pk_mul_f32 v[228:229], v[228:229], v[228:229]
	v_sqrt_f32_e32 v226, v180
	v_sub_f32_e32 v180, 1.0, v227
	v_rcp_f32_e32 v169, v221
	v_sub_f32_e32 v221, 1.0, v228
	v_sqrt_f32_e32 v227, v180
	v_sqrt_f32_e32 v228, v221
	v_sub_f32_e32 v221, 1.0, v229
	v_add_f32_e32 v156, 1.0, v156
	v_add_f32_e32 v157, 1.0, v157
	v_rcp_f32_e32 v171, v171
	v_sqrt_f32_e32 v229, v221
	v_rcp_f32_e32 v156, v156
	v_rcp_f32_e32 v157, v157
	v_add_f32_e32 v158, 1.0, v158
	v_add_f32_e32 v159, 1.0, v159
	v_rcp_f32_e32 v158, v158
	v_rcp_f32_e32 v159, v159
	v_pk_mul_f32 v[168:169], v[168:169], v[226:227]
	v_lshlrev_b32_e32 v180, 16, v181
	v_pk_mul_f32 v[168:169], v[168:169], v[224:225]
	v_and_b32_e32 v181, 0xffff0000, v181
; __device__ __forceinline__ unsigned cvt_pk_bf16(float lo, float hi) { unsigned r; asm volatile("v_cvt_pk_bf16_f32 %0, %1, %2" : "=v"(r) : "v"(lo), "v"(hi)); return r; }
; __device__ __forceinline__ float bf_lo(unsigned w) { return __uint_as_float(w << 16); }
; __device__ __forceinline__ float bf_hi(unsigned w) { return __uint_as_float(w & 0xffff0000u); }
;     __device__ __forceinline__ void operator()(EPI_ARGS) const {
;     ...
;                     const unsigned w0 = n ? vv[ai][m].z : vv[ai][m].x, w1 = n ? vv[ai][m].w : vv[ai][m].y;
;                     const f32x4 vx = (f32x4){bf_lo(w0), bf_hi(w0), bf_lo(w1), bf_hi(w1)};
;                     const f32x4 r = sigmoid4(acc[ai][0][m][n] + ba[n]), ig = sigmoid4(acc[ai][1][m][n] + bi[n]);
;                     const f32x4 la = sp[n] * r * (-1.4426950409f);
;                     f32x4 av;
; #pragma unroll
;                     for (int j = 0; j < 4; ++j) av[j] = __builtin_amdgcn_exp2f(la[j]);
;                     const f32x4 om = 1.0f - av * av; f32x4 sq;
; #pragma unroll
;                     for (int j = 0; j < 4; ++j) sq[j] = __builtin_amdgcn_sqrtf(om[j]);
;                     const f32x4 bx = sq * ig * vx;
;                     u32x4 w; w.x = cvt_pk_bf16(la[0], bx[0]); w.y = cvt_pk_bf16(la[1], bx[1]); w.z = cvt_pk_bf16(la[2], bx[2]); w.w = cvt_pk_bf16(la[3], bx[3]);
;                     *(u32x4*)(AB + (size_t)row * LW + c0 + 4 * n) = w;
; __global__ void __launch_bounds__(NTHR, 2) hybrid_block_fwd(Args a) {
;     ...
;         for (int i = 0; i < CH_L; ++i) { const u32x2 q = pab[(size_t)i * (LW / 2)];
;             const f32x2 av = (f32x2){__builtin_amdgcn_exp2f(bf_lo(q.x)), __builtin_amdgcn_exp2f(bf_lo(q.y))}, bv = (f32x2){bf_hi(q.x), bf_hi(q.y)}; P = P * av; H = av * H + bv; }
	v_pk_mul_f32 v[170:171], v[170:171], v[228:229]
	v_cvt_pk_bf16_f32 v160, v160, v168
	v_cvt_pk_bf16_f32 v161, v161, v169
	v_lshl_add_u64 v[168:169], s[92:93], 0, v[222:223]
	v_pk_mul_f32 v[156:157], v[64:65], v[156:157]
	v_pk_mul_f32 v[170:171], v[170:171], v[180:181]
	v_lshl_add_u64 v[168:169], v[168:169], 0, v[196:197]
	v_cvt_pk_bf16_f32 v162, v162, v170
	v_cvt_pk_bf16_f32 v163, v163, v171
	v_pk_add_f32 v[152:153], v[152:153], v[72:73]
	v_pk_mul_f32 v[158:159], v[66:67], v[158:159]
	v_pk_mul_f32 v[156:157], v[156:157], s[62:63] op_sel_hi:[1,0]
	v_pk_add_f32 v[144:145], v[144:145], v[100:101]
	global_store_dwordx4 v[168:169], v[160:163], off
	v_lshlrev_b32_e32 v221, 16, v160
	v_lshlrev_b32_e32 v222, 16, v161
	v_lshlrev_b32_e32 v223, 16, v162
	v_lshlrev_b32_e32 v224, 16, v163
	v_and_b32_e32 v225, 0xffff0000, v160
	v_and_b32_e32 v226, 0xffff0000, v161
	v_and_b32_e32 v227, 0xffff0000, v162
	v_and_b32_e32 v228, 0xffff0000, v163
	v_exp_f32_e32 v221, v221
	v_exp_f32_e32 v222, v222
	v_exp_f32_e32 v223, v223
	v_exp_f32_e32 v224, v224
	v_fmac_f32_dpp v225, v225, v221 row_shr:1 row_mask:0xf bank_mask:0xf
	v_fmac_f32_dpp v226, v226, v222 row_shr:1 row_mask:0xf bank_mask:0xf
	v_fmac_f32_dpp v227, v227, v223 row_shr:1 row_mask:0xf bank_mask:0xf
	v_fmac_f32_dpp v228, v228, v224 row_shr:1 row_mask:0xf bank_mask:0xf
	v_mul_f32_dpp v221, v221, v221 row_shr:1 row_mask:0xf bank_mask:0xf
	v_mul_f32_dpp v222, v222, v222 row_shr:1 row_mask:0xf bank_mask:0xf
	v_mul_f32_dpp v223, v223, v223 row_shr:1 row_mask:0xf bank_mask:0xf
	v_mul_f32_dpp v224, v224, v224 row_shr:1 row_mask:0xf bank_mask:0xf
	v_fmac_f32_dpp v225, v225, v221 row_shr:2 row_mask:0xf bank_mask:0xf
	v_fmac_f32_dpp v226, v226, v222 row_shr:2 row_mask:0xf bank_mask:0xf
	v_fmac_f32_dpp v227, v227, v223 row_shr:2 row_mask:0xf bank_mask:0xf
	v_fmac_f32_dpp v228, v228, v224 row_shr:2 row_mask:0xf bank_mask:0xf
	v_mul_f32_dpp v221, v221, v221 row_shr:2 row_mask:0xf bank_mask:0xf
	v_mul_f32_dpp v222, v222, v222 row_shr:2 row_mask:0xf bank_mask:0xf
	v_mul_f32_dpp v223, v223, v223 row_shr:2 row_mask:0xf bank_mask:0xf
	v_mul_f32_dpp v224, v224, v224 row_shr:2 row_mask:0xf bank_mask:0xf
	v_fmac_f32_dpp v225, v225, v221 row_shr:4 row_mask:0xf bank_mask:0xf
	v_fmac_f32_dpp v226, v226, v222 row_shr:4 row_mask:0xf bank_mask:0xf
	v_fmac_f32_dpp v227, v227, v223 row_shr:4 row_mask:0xf bank_mask:0xf
	v_fmac_f32_dpp v228, v228, v224 row_shr:4 row_mask:0xf bank_mask:0xf
	v_mul_f32_dpp v221, v221, v221 row_shr:4 row_mask:0xf bank_mask:0xf
	v_mul_f32_dpp v222, v222, v222 row_shr:4 row_mask:0xf bank_mask:0xf
	v_mul_f32_dpp v223, v223, v223 row_shr:4 row_mask:0xf bank_mask:0xf
	v_mul_f32_dpp v224, v224, v224 row_shr:4 row_mask:0xf bank_mask:0xf
	v_fmac_f32_dpp v225, v225, v221 row_shr:8 row_mask:0xf bank_mask:0xf
	v_fmac_f32_dpp v226, v226, v222 row_shr:8 row_mask:0xf bank_mask:0xf
	v_fmac_f32_dpp v227, v227, v223 row_shr:8 row_mask:0xf bank_mask:0xf
	v_fmac_f32_dpp v228, v228, v224 row_shr:8 row_mask:0xf bank_mask:0xf
	v_mul_f32_dpp v221, v221, v221 row_shr:8 row_mask:0xf bank_mask:0xf
	v_mul_f32_dpp v222, v222, v222 row_shr:8 row_mask:0xf bank_mask:0xf
	v_mul_f32_dpp v223, v223, v223 row_shr:8 row_mask:0xf bank_mask:0xf
	v_mul_f32_dpp v224, v224, v224 row_shr:8 row_mask:0xf bank_mask:0xf
	v_mov_b32_e32 v230, v221
	v_mov_b32_e32 v231, v222
	v_mov_b32_e32 v232, v223
	v_mov_b32_e32 v233, v224
	v_mov_b32_e32 v234, v225
	v_mov_b32_e32 v235, v226
	v_mov_b32_e32 v236, v227
	v_mov_b32_e32 v237, v228
	v_pk_add_f32 v[154:155], v[154:155], v[74:75]
	v_mul_f32_e32 v152, 0xbfb8aa3b, v152
	v_mul_f32_e32 v153, 0xbfb8aa3b, v153
	v_pk_mul_f32 v[158:159], v[158:159], s[62:63] op_sel_hi:[1,0]
	v_exp_f32_e32 v162, v156
	v_exp_f32_e32 v163, v157
	v_pk_add_f32 v[146:147], v[146:147], v[102:103]
	v_mul_f32_e32 v144, 0xbfb8aa3b, v144
	v_mul_f32_e32 v145, 0xbfb8aa3b, v145
	v_exp_f32_e32 v152, v152
	v_exp_f32_e32 v153, v153
	v_mul_f32_e32 v154, 0xbfb8aa3b, v154
	v_mul_f32_e32 v155, 0xbfb8aa3b, v155
	v_exp_f32_e32 v170, v158
	v_exp_f32_e32 v171, v159
	v_exp_f32_e32 v144, v144
	v_exp_f32_e32 v145, v145
	v_mul_f32_e32 v146, 0xbfb8aa3b, v146
	v_mul_f32_e32 v147, 0xbfb8aa3b, v147
	v_exp_f32_e32 v154, v154
	v_exp_f32_e32 v155, v155
	v_exp_f32_e32 v146, v146
	v_exp_f32_e32 v147, v147
	v_pk_mul_f32 v[162:163], v[162:163], v[162:163]
	v_add_f32_e32 v152, 1.0, v152
	v_add_f32_e32 v153, 1.0, v153
	v_pk_mul_f32 v[170:171], v[170:171], v[170:171]
	v_sub_f32_e32 v162, 1.0, v162
	v_sub_f32_e32 v163, 1.0, v163
	v_add_f32_e32 v144, 1.0, v144
	v_add_f32_e32 v145, 1.0, v145
	v_rcp_f32_e32 v152, v152
	v_rcp_f32_e32 v153, v153
	v_add_f32_e32 v154, 1.0, v154
	v_add_f32_e32 v155, 1.0, v155
	v_sqrt_f32_e32 v162, v162
	v_sub_f32_e32 v170, 1.0, v170
	v_sub_f32_e32 v171, 1.0, v171
	v_sqrt_f32_e32 v163, v163
	v_rcp_f32_e32 v144, v144
	v_rcp_f32_e32 v145, v145
	v_add_f32_e32 v146, 1.0, v146
	v_add_f32_e32 v147, 1.0, v147
	v_rcp_f32_e32 v154, v154
	v_rcp_f32_e32 v155, v155
	v_sqrt_f32_e32 v170, v170
	v_sqrt_f32_e32 v171, v171
	v_rcp_f32_e32 v146, v146
	v_rcp_f32_e32 v147, v147
	v_lshlrev_b32_e32 v160, 16, v182
	v_and_b32_e32 v161, 0xffff0000, v182
	v_pk_mul_f32 v[152:153], v[152:153], v[162:163]
	v_pk_mul_f32 v[144:145], v[88:89], v[144:145]
	v_lshlrev_b32_e32 v180, 16, v183
	v_and_b32_e32 v181, 0xffff0000, v183
	v_pk_mul_f32 v[154:155], v[154:155], v[170:171]
	v_pk_mul_f32 v[152:153], v[152:153], v[160:161]
	v_pk_add_f32 v[140:141], v[140:141], v[92:93]
	v_pk_mul_f32 v[146:147], v[90:91], v[146:147]
	v_pk_mul_f32 v[144:145], v[144:145], s[62:63] op_sel_hi:[1,0]
	v_pk_mul_f32 v[154:155], v[154:155], v[180:181]
	v_cvt_pk_bf16_f32 v152, v156, v152
	v_cvt_pk_bf16_f32 v153, v157, v153
; __device__ __forceinline__ unsigned cvt_pk_bf16(float lo, float hi) { unsigned r; asm volatile("v_cvt_pk_bf16_f32 %0, %1, %2" : "=v"(r) : "v"(lo), "v"(hi)); return r; }
; __device__ __forceinline__ float bf_lo(unsigned w) { return __uint_as_float(w << 16); }
; __device__ __forceinline__ float bf_hi(unsigned w) { return __uint_as_float(w & 0xffff0000u); }
;     __device__ __forceinline__ void operator()(EPI_ARGS) const {
;     ...
;                     const unsigned w0 = n ? vv[ai][m].z : vv[ai][m].x, w1 = n ? vv[ai][m].w : vv[ai][m].y;
;                     const f32x4 vx = (f32x4){bf_lo(w0), bf_hi(w0), bf_lo(w1), bf_hi(w1)};
;                     const f32x4 r = sigmoid4(acc[ai][0][m][n] + ba[n]), ig = sigmoid4(acc[ai][1][m][n] + bi[n]);
;                     const f32x4 la = sp[n] * r * (-1.4426950409f);
;                     f32x4 av;
; #pragma unroll
;                     for (int j = 0; j < 4; ++j) av[j] = __builtin_amdgcn_exp2f(la[j]);
;                     const f32x4 om = 1.0f - av * av; f32x4 sq;
; #pragma unroll
;                     for (int j = 0; j < 4; ++j) sq[j] = __builtin_amdgcn_sqrtf(om[j]);
;                     const f32x4 bx = sq * ig * vx;
;                     u32x4 w; w.x = cvt_pk_bf16(la[0], bx[0]); w.y = cvt_pk_bf16(la[1], bx[1]); w.z = cvt_pk_bf16(la[2], bx[2]); w.w = cvt_pk_bf16(la[3], bx[3]);
;                     *(u32x4*)(AB + (size_t)row * LW + c0 + 4 * n) = w;
; __global__ void __launch_bounds__(NTHR, 2) hybrid_block_fwd(Args a) {
;     ...
;         for (int i = 0; i < CH_L; ++i) { const u32x2 q = pab[(size_t)i * (LW / 2)];
;             const f32x2 av = (f32x2){__builtin_amdgcn_exp2f(bf_lo(q.x)), __builtin_amdgcn_exp2f(bf_lo(q.y))}, bv = (f32x2){bf_hi(q.x), bf_hi(q.y)}; P = P * av; H = av * H + bv; }
	v_pk_add_f32 v[142:143], v[142:143], v[94:95]
	v_mul_f32_e32 v140, 0xbfb8aa3b, v140
	v_mul_f32_e32 v141, 0xbfb8aa3b, v141
	v_pk_mul_f32 v[146:147], v[146:147], s[62:63] op_sel_hi:[1,0]
	v_exp_f32_e32 v156, v144
	v_exp_f32_e32 v157, v145
	v_cvt_pk_bf16_f32 v154, v158, v154
	v_cvt_pk_bf16_f32 v155, v159, v155
	v_exp_f32_e32 v140, v140
	v_exp_f32_e32 v141, v141
	v_mul_f32_e32 v142, 0xbfb8aa3b, v142
	v_mul_f32_e32 v143, 0xbfb8aa3b, v143
	v_exp_f32_e32 v158, v146
	v_exp_f32_e32 v159, v147
	v_pk_add_f32 v[136:137], v[136:137], v[80:81]
	v_exp_f32_e32 v142, v142
	v_exp_f32_e32 v143, v143
	v_pk_add_f32 v[138:139], v[138:139], v[82:83]
	v_mul_f32_e32 v136, 0xbfb8aa3b, v136
	v_mul_f32_e32 v137, 0xbfb8aa3b, v137
	v_exp_f32_e32 v136, v136
	v_exp_f32_e32 v137, v137
	v_mul_f32_e32 v138, 0xbfb8aa3b, v138
	v_mul_f32_e32 v139, 0xbfb8aa3b, v139
	v_pk_mul_f32 v[156:157], v[156:157], v[156:157]
	v_exp_f32_e32 v138, v138
	v_exp_f32_e32 v139, v139
	v_add_f32_e32 v140, 1.0, v140
	v_add_f32_e32 v141, 1.0, v141
	v_pk_mul_f32 v[158:159], v[158:159], v[158:159]
	v_sub_f32_e32 v156, 1.0, v156
	v_sub_f32_e32 v157, 1.0, v157
	v_rcp_f32_e32 v140, v140
	v_rcp_f32_e32 v141, v141
	v_add_f32_e32 v142, 1.0, v142
	v_add_f32_e32 v143, 1.0, v143
	v_sqrt_f32_e32 v156, v156
	v_sub_f32_e32 v158, 1.0, v158
	v_sub_f32_e32 v159, 1.0, v159
	v_sqrt_f32_e32 v157, v157
	v_rcp_f32_e32 v142, v142
	v_rcp_f32_e32 v143, v143
	v_sqrt_f32_e32 v158, v158
	v_sqrt_f32_e32 v159, v159
	v_add_f32_e32 v136, 1.0, v136
	v_add_f32_e32 v137, 1.0, v137
	v_rcp_f32_e32 v136, v136
	v_rcp_f32_e32 v137, v137
	v_add_f32_e32 v138, 1.0, v138
	v_add_f32_e32 v139, 1.0, v139
	v_rcp_f32_e32 v138, v138
	v_rcp_f32_e32 v139, v139
	global_store_dwordx4 v[168:169], v[152:155], off offset:16
	v_lshlrev_b32_e32 v221, 16, v152
	v_lshlrev_b32_e32 v222, 16, v153
	v_lshlrev_b32_e32 v223, 16, v154
	v_lshlrev_b32_e32 v224, 16, v155
	v_and_b32_e32 v225, 0xffff0000, v152
	v_and_b32_e32 v226, 0xffff0000, v153
	v_and_b32_e32 v227, 0xffff0000, v154
	v_and_b32_e32 v228, 0xffff0000, v155
	v_exp_f32_e32 v221, v221
	v_exp_f32_e32 v222, v222
	v_exp_f32_e32 v223, v223
	v_exp_f32_e32 v224, v224
	v_fmac_f32_dpp v225, v225, v221 row_shr:1 row_mask:0xf bank_mask:0xf
	v_fmac_f32_dpp v226, v226, v222 row_shr:1 row_mask:0xf bank_mask:0xf
	v_fmac_f32_dpp v227, v227, v223 row_shr:1 row_mask:0xf bank_mask:0xf
	v_fmac_f32_dpp v228, v228, v224 row_shr:1 row_mask:0xf bank_mask:0xf
	v_mul_f32_dpp v221, v221, v221 row_shr:1 row_mask:0xf bank_mask:0xf
	v_mul_f32_dpp v222, v222, v222 row_shr:1 row_mask:0xf bank_mask:0xf
	v_mul_f32_dpp v223, v223, v223 row_shr:1 row_mask:0xf bank_mask:0xf
	v_mul_f32_dpp v224, v224, v224 row_shr:1 row_mask:0xf bank_mask:0xf
	v_fmac_f32_dpp v225, v225, v221 row_shr:2 row_mask:0xf bank_mask:0xf
	v_fmac_f32_dpp v226, v226, v222 row_shr:2 row_mask:0xf bank_mask:0xf
	v_fmac_f32_dpp v227, v227, v223 row_shr:2 row_mask:0xf bank_mask:0xf
	v_fmac_f32_dpp v228, v228, v224 row_shr:2 row_mask:0xf bank_mask:0xf
	v_mul_f32_dpp v221, v221, v221 row_shr:2 row_mask:0xf bank_mask:0xf
	v_mul_f32_dpp v222, v222, v222 row_shr:2 row_mask:0xf bank_mask:0xf
	v_mul_f32_dpp v223, v223, v223 row_shr:2 row_mask:0xf bank_mask:0xf
	v_mul_f32_dpp v224, v224, v224 row_shr:2 row_mask:0xf bank_mask:0xf
	v_fmac_f32_dpp v225, v225, v221 row_shr:4 row_mask:0xf bank_mask:0xf
	v_fmac_f32_dpp v226, v226, v222 row_shr:4 row_mask:0xf bank_mask:0xf
	v_fmac_f32_dpp v227, v227, v223 row_shr:4 row_mask:0xf bank_mask:0xf
	v_fmac_f32_dpp v228, v228, v224 row_shr:4 row_mask:0xf bank_mask:0xf
	v_mul_f32_dpp v221, v221, v221 row_shr:4 row_mask:0xf bank_mask:0xf
	v_mul_f32_dpp v222, v222, v222 row_shr:4 row_mask:0xf bank_mask:0xf
	v_mul_f32_dpp v223, v223, v223 row_shr:4 row_mask:0xf bank_mask:0xf
	v_mul_f32_dpp v224, v224, v224 row_shr:4 row_mask:0xf bank_mask:0xf
	v_fmac_f32_dpp v225, v225, v221 row_shr:8 row_mask:0xf bank_mask:0xf
	v_fmac_f32_dpp v226, v226, v222 row_shr:8 row_mask:0xf bank_mask:0xf
	v_fmac_f32_dpp v227, v227, v223 row_shr:8 row_mask:0xf bank_mask:0xf
	v_fmac_f32_dpp v228, v228, v224 row_shr:8 row_mask:0xf bank_mask:0xf
	v_mul_f32_dpp v221, v221, v221 row_shr:8 row_mask:0xf bank_mask:0xf
	v_mul_f32_dpp v222, v222, v222 row_shr:8 row_mask:0xf bank_mask:0xf
	v_mul_f32_dpp v223, v223, v223 row_shr:8 row_mask:0xf bank_mask:0xf
	v_mul_f32_dpp v224, v224, v224 row_shr:8 row_mask:0xf bank_mask:0xf
	v_mov_b32_e32 v238, v221
	v_mov_b32_e32 v239, v222
	v_mov_b32_e32 v240, v223
	v_mov_b32_e32 v241, v224
	v_mov_b32_e32 v242, v225
	v_mov_b32_e32 v243, v226
	v_mov_b32_e32 v244, v227
	v_mov_b32_e32 v245, v228
	v_pk_mul_f32 v[140:141], v[140:141], v[156:157]
	v_lshlrev_b32_e32 v160, 16, v177
	v_lshlrev_b32_e32 v154, 16, v176
	v_and_b32_e32 v155, 0xffff0000, v176
	v_lshlrev_b64 v[152:153], 13, v[210:211]
	v_and_b32_e32 v161, 0xffff0000, v177
	v_pk_mul_f32 v[142:143], v[142:143], v[158:159]
	v_pk_mul_f32 v[140:141], v[140:141], v[154:155]
	v_pk_mul_f32 v[142:143], v[142:143], v[160:161]
	v_cvt_pk_bf16_f32 v140, v144, v140
	v_cvt_pk_bf16_f32 v141, v145, v141
	v_lshl_add_u64 v[144:145], s[92:93], 0, v[152:153]
	v_pk_mul_f32 v[136:137], v[64:65], v[136:137]
	v_cvt_pk_bf16_f32 v142, v146, v142
	v_cvt_pk_bf16_f32 v143, v147, v143
	v_lshl_add_u64 v[144:145], v[144:145], 0, v[196:197]
	v_pk_add_f32 v[132:133], v[132:133], v[72:73]
	v_pk_mul_f32 v[138:139], v[66:67], v[138:139]
	v_pk_mul_f32 v[136:137], v[136:137], s[62:63] op_sel_hi:[1,0]
	v_pk_add_f32 v[124:125], v[124:125], v[100:101]
	global_store_dwordx4 v[144:145], v[140:143], off
	v_lshlrev_b32_e32 v221, 16, v140
	v_lshlrev_b32_e32 v222, 16, v141
	v_lshlrev_b32_e32 v223, 16, v142
	v_lshlrev_b32_e32 v224, 16, v143
; __device__ __forceinline__ unsigned cvt_pk_bf16(float lo, float hi) { unsigned r; asm volatile("v_cvt_pk_bf16_f32 %0, %1, %2" : "=v"(r) : "v"(lo), "v"(hi)); return r; }
; __device__ __forceinline__ float bf_lo(unsigned w) { return __uint_as_float(w << 16); }
; __device__ __forceinline__ float bf_hi(unsigned w) { return __uint_as_float(w & 0xffff0000u); }
;     __device__ __forceinline__ void operator()(EPI_ARGS) const {
;     ...
;                     const unsigned w0 = n ? vv[ai][m].z : vv[ai][m].x, w1 = n ? vv[ai][m].w : vv[ai][m].y;
;                     const f32x4 vx = (f32x4){bf_lo(w0), bf_hi(w0), bf_lo(w1), bf_hi(w1)};
;                     const f32x4 r = sigmoid4(acc[ai][0][m][n] + ba[n]), ig = sigmoid4(acc[ai][1][m][n] + bi[n]);
;                     const f32x4 la = sp[n] * r * (-1.4426950409f);
;                     f32x4 av;
; #pragma unroll
;                     for (int j = 0; j < 4; ++j) av[j] = __builtin_amdgcn_exp2f(la[j]);
;                     const f32x4 om = 1.0f - av * av; f32x4 sq;
; #pragma unroll
;                     for (int j = 0; j < 4; ++j) sq[j] = __builtin_amdgcn_sqrtf(om[j]);
;                     const f32x4 bx = sq * ig * vx;
;                     u32x4 w; w.x = cvt_pk_bf16(la[0], bx[0]); w.y = cvt_pk_bf16(la[1], bx[1]); w.z = cvt_pk_bf16(la[2], bx[2]); w.w = cvt_pk_bf16(la[3], bx[3]);
;                     *(u32x4*)(AB + (size_t)row * LW + c0 + 4 * n) = w;
; __global__ void __launch_bounds__(NTHR, 2) hybrid_block_fwd(Args a) {
;     ...
;         for (int i = 0; i < CH_L; ++i) { const u32x2 q = pab[(size_t)i * (LW / 2)];
;             const f32x2 av = (f32x2){__builtin_amdgcn_exp2f(bf_lo(q.x)), __builtin_amdgcn_exp2f(bf_lo(q.y))}, bv = (f32x2){bf_hi(q.x), bf_hi(q.y)}; P = P * av; H = av * H + bv; }
	v_and_b32_e32 v225, 0xffff0000, v140
	v_and_b32_e32 v226, 0xffff0000, v141
	v_and_b32_e32 v227, 0xffff0000, v142
	v_and_b32_e32 v228, 0xffff0000, v143
	v_exp_f32_e32 v221, v221
	v_exp_f32_e32 v222, v222
	v_exp_f32_e32 v223, v223
	v_exp_f32_e32 v224, v224
	v_fmac_f32_dpp v225, v225, v221 row_shr:1 row_mask:0xf bank_mask:0xf
	v_fmac_f32_dpp v226, v226, v222 row_shr:1 row_mask:0xf bank_mask:0xf
	v_fmac_f32_dpp v227, v227, v223 row_shr:1 row_mask:0xf bank_mask:0xf
	v_fmac_f32_dpp v228, v228, v224 row_shr:1 row_mask:0xf bank_mask:0xf
	v_mul_f32_dpp v221, v221, v221 row_shr:1 row_mask:0xf bank_mask:0xf
	v_mul_f32_dpp v222, v222, v222 row_shr:1 row_mask:0xf bank_mask:0xf
	v_mul_f32_dpp v223, v223, v223 row_shr:1 row_mask:0xf bank_mask:0xf
	v_mul_f32_dpp v224, v224, v224 row_shr:1 row_mask:0xf bank_mask:0xf
	v_fmac_f32_dpp v225, v225, v221 row_shr:2 row_mask:0xf bank_mask:0xf
	v_fmac_f32_dpp v226, v226, v222 row_shr:2 row_mask:0xf bank_mask:0xf
	v_fmac_f32_dpp v227, v227, v223 row_shr:2 row_mask:0xf bank_mask:0xf
	v_fmac_f32_dpp v228, v228, v224 row_shr:2 row_mask:0xf bank_mask:0xf
	v_mul_f32_dpp v221, v221, v221 row_shr:2 row_mask:0xf bank_mask:0xf
	v_mul_f32_dpp v222, v222, v222 row_shr:2 row_mask:0xf bank_mask:0xf
	v_mul_f32_dpp v223, v223, v223 row_shr:2 row_mask:0xf bank_mask:0xf
	v_mul_f32_dpp v224, v224, v224 row_shr:2 row_mask:0xf bank_mask:0xf
	v_fmac_f32_dpp v225, v225, v221 row_shr:4 row_mask:0xf bank_mask:0xf
	v_fmac_f32_dpp v226, v226, v222 row_shr:4 row_mask:0xf bank_mask:0xf
	v_fmac_f32_dpp v227, v227, v223 row_shr:4 row_mask:0xf bank_mask:0xf
	v_fmac_f32_dpp v228, v228, v224 row_shr:4 row_mask:0xf bank_mask:0xf
	v_mul_f32_dpp v221, v221, v221 row_shr:4 row_mask:0xf bank_mask:0xf
	v_mul_f32_dpp v222, v222, v222 row_shr:4 row_mask:0xf bank_mask:0xf
	v_mul_f32_dpp v223, v223, v223 row_shr:4 row_mask:0xf bank_mask:0xf
	v_mul_f32_dpp v224, v224, v224 row_shr:4 row_mask:0xf bank_mask:0xf
	v_fmac_f32_dpp v225, v225, v221 row_shr:8 row_mask:0xf bank_mask:0xf
	v_fmac_f32_dpp v226, v226, v222 row_shr:8 row_mask:0xf bank_mask:0xf
	v_fmac_f32_dpp v227, v227, v223 row_shr:8 row_mask:0xf bank_mask:0xf
	v_fmac_f32_dpp v228, v228, v224 row_shr:8 row_mask:0xf bank_mask:0xf
	v_mul_f32_dpp v221, v221, v221 row_shr:8 row_mask:0xf bank_mask:0xf
	v_mul_f32_dpp v222, v222, v222 row_shr:8 row_mask:0xf bank_mask:0xf
	v_mul_f32_dpp v223, v223, v223 row_shr:8 row_mask:0xf bank_mask:0xf
	v_mul_f32_dpp v224, v224, v224 row_shr:8 row_mask:0xf bank_mask:0xf
	v_fma_f32 v234, v234, v221, v225
	v_fma_f32 v235, v235, v222, v226
	v_fma_f32 v236, v236, v223, v227
	v_fma_f32 v237, v237, v224, v228
	v_mul_f32_e32 v230, v230, v221
	v_mul_f32_e32 v231, v231, v222
	v_mul_f32_e32 v232, v232, v223
	v_mul_f32_e32 v233, v233, v224
	v_pk_add_f32 v[134:135], v[134:135], v[74:75]
	v_mul_f32_e32 v132, 0xbfb8aa3b, v132
	v_mul_f32_e32 v133, 0xbfb8aa3b, v133
	v_pk_mul_f32 v[138:139], v[138:139], s[62:63] op_sel_hi:[1,0]
	v_exp_f32_e32 v142, v136
	v_exp_f32_e32 v143, v137
	v_pk_add_f32 v[126:127], v[126:127], v[102:103]
	v_mul_f32_e32 v124, 0xbfb8aa3b, v124
	v_mul_f32_e32 v125, 0xbfb8aa3b, v125
	v_exp_f32_e32 v132, v132
	v_exp_f32_e32 v133, v133
	v_mul_f32_e32 v134, 0xbfb8aa3b, v134
	v_mul_f32_e32 v135, 0xbfb8aa3b, v135
	v_exp_f32_e32 v146, v138
	v_exp_f32_e32 v147, v139
	v_exp_f32_e32 v124, v124
	v_exp_f32_e32 v125, v125
	v_mul_f32_e32 v126, 0xbfb8aa3b, v126
	v_mul_f32_e32 v127, 0xbfb8aa3b, v127
	v_exp_f32_e32 v134, v134
	v_exp_f32_e32 v135, v135
	v_exp_f32_e32 v126, v126
	v_exp_f32_e32 v127, v127
	v_pk_mul_f32 v[142:143], v[142:143], v[142:143]
	v_add_f32_e32 v132, 1.0, v132
	v_add_f32_e32 v133, 1.0, v133
	v_pk_mul_f32 v[146:147], v[146:147], v[146:147]
	v_sub_f32_e32 v142, 1.0, v142
	v_sub_f32_e32 v143, 1.0, v143
	v_add_f32_e32 v124, 1.0, v124
	v_add_f32_e32 v125, 1.0, v125
	v_rcp_f32_e32 v132, v132
	v_rcp_f32_e32 v133, v133
	v_add_f32_e32 v134, 1.0, v134
	v_add_f32_e32 v135, 1.0, v135
	v_sqrt_f32_e32 v142, v142
	v_sub_f32_e32 v146, 1.0, v146
	v_sub_f32_e32 v147, 1.0, v147
	v_sqrt_f32_e32 v143, v143
	v_rcp_f32_e32 v124, v124
	v_rcp_f32_e32 v125, v125
	v_add_f32_e32 v126, 1.0, v126
	v_add_f32_e32 v127, 1.0, v127
	v_rcp_f32_e32 v134, v134
	v_rcp_f32_e32 v135, v135
	v_sqrt_f32_e32 v146, v146
	v_sqrt_f32_e32 v147, v147
	v_rcp_f32_e32 v126, v126
	v_rcp_f32_e32 v127, v127
	v_lshlrev_b32_e32 v140, 16, v178
	v_and_b32_e32 v141, 0xffff0000, v178
	v_pk_mul_f32 v[132:133], v[132:133], v[142:143]
	v_pk_mul_f32 v[124:125], v[88:89], v[124:125]
	v_lshlrev_b32_e32 v152, 16, v179
	v_and_b32_e32 v153, 0xffff0000, v179
	v_pk_mul_f32 v[134:135], v[134:135], v[146:147]
	v_pk_mul_f32 v[132:133], v[132:133], v[140:141]
	v_pk_add_f32 v[120:121], v[120:121], v[92:93]
	v_pk_mul_f32 v[126:127], v[90:91], v[126:127]
	v_pk_mul_f32 v[124:125], v[124:125], s[62:63] op_sel_hi:[1,0]
	v_pk_mul_f32 v[134:135], v[134:135], v[152:153]
	v_cvt_pk_bf16_f32 v132, v136, v132
	v_cvt_pk_bf16_f32 v133, v137, v133
	v_pk_add_f32 v[122:123], v[122:123], v[94:95]
	v_mul_f32_e32 v120, 0xbfb8aa3b, v120
	v_mul_f32_e32 v121, 0xbfb8aa3b, v121
	v_pk_mul_f32 v[126:127], v[126:127], s[62:63] op_sel_hi:[1,0]
	v_exp_f32_e32 v136, v124
	v_exp_f32_e32 v137, v125
	v_cvt_pk_bf16_f32 v134, v138, v134
	v_cvt_pk_bf16_f32 v135, v139, v135
	v_exp_f32_e32 v120, v120
	v_exp_f32_e32 v121, v121
	v_mul_f32_e32 v122, 0xbfb8aa3b, v122
	v_mul_f32_e32 v123, 0xbfb8aa3b, v123
	v_exp_f32_e32 v138, v126
	v_exp_f32_e32 v139, v127
	v_pk_add_f32 v[116:117], v[116:117], v[80:81]
	v_exp_f32_e32 v122, v122
	v_exp_f32_e32 v123, v123
	v_pk_add_f32 v[118:119], v[118:119], v[82:83]
	v_mul_f32_e32 v116, 0xbfb8aa3b, v116
	v_mul_f32_e32 v117, 0xbfb8aa3b, v117
; __device__ __forceinline__ unsigned cvt_pk_bf16(float lo, float hi) { unsigned r; asm volatile("v_cvt_pk_bf16_f32 %0, %1, %2" : "=v"(r) : "v"(lo), "v"(hi)); return r; }
; __device__ __forceinline__ float bf_lo(unsigned w) { return __uint_as_float(w << 16); }
; __device__ __forceinline__ float bf_hi(unsigned w) { return __uint_as_float(w & 0xffff0000u); }
;     __device__ __forceinline__ void operator()(EPI_ARGS) const {
;     ...
;                     const unsigned w0 = n ? vv[ai][m].z : vv[ai][m].x, w1 = n ? vv[ai][m].w : vv[ai][m].y;
;                     const f32x4 vx = (f32x4){bf_lo(w0), bf_hi(w0), bf_lo(w1), bf_hi(w1)};
;                     const f32x4 r = sigmoid4(acc[ai][0][m][n] + ba[n]), ig = sigmoid4(acc[ai][1][m][n] + bi[n]);
;                     const f32x4 la = sp[n] * r * (-1.4426950409f);
;                     f32x4 av;
; #pragma unroll
;                     for (int j = 0; j < 4; ++j) av[j] = __builtin_amdgcn_exp2f(la[j]);
;                     const f32x4 om = 1.0f - av * av; f32x4 sq;
; #pragma unroll
;                     for (int j = 0; j < 4; ++j) sq[j] = __builtin_amdgcn_sqrtf(om[j]);
;                     const f32x4 bx = sq * ig * vx;
;                     u32x4 w; w.x = cvt_pk_bf16(la[0], bx[0]); w.y = cvt_pk_bf16(la[1], bx[1]); w.z = cvt_pk_bf16(la[2], bx[2]); w.w = cvt_pk_bf16(la[3], bx[3]);
;                     *(u32x4*)(AB + (size_t)row * LW + c0 + 4 * n) = w;
; __global__ void __launch_bounds__(NTHR, 2) hybrid_block_fwd(Args a) {
;     ...
;         for (int i = 0; i < CH_L; ++i) { const u32x2 q = pab[(size_t)i * (LW / 2)];
;             const f32x2 av = (f32x2){__builtin_amdgcn_exp2f(bf_lo(q.x)), __builtin_amdgcn_exp2f(bf_lo(q.y))}, bv = (f32x2){bf_hi(q.x), bf_hi(q.y)}; P = P * av; H = av * H + bv; }
	v_exp_f32_e32 v116, v116
	v_exp_f32_e32 v117, v117
	v_mul_f32_e32 v118, 0xbfb8aa3b, v118
	v_mul_f32_e32 v119, 0xbfb8aa3b, v119
	v_pk_mul_f32 v[136:137], v[136:137], v[136:137]
	v_exp_f32_e32 v118, v118
	v_exp_f32_e32 v119, v119
	v_add_f32_e32 v120, 1.0, v120
	v_add_f32_e32 v121, 1.0, v121
	v_pk_mul_f32 v[138:139], v[138:139], v[138:139]
	v_sub_f32_e32 v136, 1.0, v136
	v_sub_f32_e32 v137, 1.0, v137
	v_rcp_f32_e32 v120, v120
	v_rcp_f32_e32 v121, v121
	v_add_f32_e32 v122, 1.0, v122
	v_add_f32_e32 v123, 1.0, v123
	v_sqrt_f32_e32 v136, v136
	v_sub_f32_e32 v138, 1.0, v138
	v_sub_f32_e32 v139, 1.0, v139
	v_sqrt_f32_e32 v137, v137
	v_rcp_f32_e32 v122, v122
	v_rcp_f32_e32 v123, v123
	v_sqrt_f32_e32 v138, v138
	v_sqrt_f32_e32 v139, v139
	v_add_f32_e32 v116, 1.0, v116
	v_add_f32_e32 v117, 1.0, v117
	v_rcp_f32_e32 v116, v116
	v_rcp_f32_e32 v117, v117
	v_add_f32_e32 v118, 1.0, v118
	v_add_f32_e32 v119, 1.0, v119
	v_rcp_f32_e32 v118, v118
	v_rcp_f32_e32 v119, v119
	global_store_dwordx4 v[144:145], v[132:135], off offset:16
	v_lshlrev_b32_e32 v221, 16, v132
	v_lshlrev_b32_e32 v222, 16, v133
	v_lshlrev_b32_e32 v223, 16, v134
	v_lshlrev_b32_e32 v224, 16, v135
	v_and_b32_e32 v225, 0xffff0000, v132
	v_and_b32_e32 v226, 0xffff0000, v133
	v_and_b32_e32 v227, 0xffff0000, v134
	v_and_b32_e32 v228, 0xffff0000, v135
	v_exp_f32_e32 v221, v221
	v_exp_f32_e32 v222, v222
	v_exp_f32_e32 v223, v223
	v_exp_f32_e32 v224, v224
	v_fmac_f32_dpp v225, v225, v221 row_shr:1 row_mask:0xf bank_mask:0xf
	v_fmac_f32_dpp v226, v226, v222 row_shr:1 row_mask:0xf bank_mask:0xf
	v_fmac_f32_dpp v227, v227, v223 row_shr:1 row_mask:0xf bank_mask:0xf
	v_fmac_f32_dpp v228, v228, v224 row_shr:1 row_mask:0xf bank_mask:0xf
	v_mul_f32_dpp v221, v221, v221 row_shr:1 row_mask:0xf bank_mask:0xf
	v_mul_f32_dpp v222, v222, v222 row_shr:1 row_mask:0xf bank_mask:0xf
	v_mul_f32_dpp v223, v223, v223 row_shr:1 row_mask:0xf bank_mask:0xf
	v_mul_f32_dpp v224, v224, v224 row_shr:1 row_mask:0xf bank_mask:0xf
	v_fmac_f32_dpp v225, v225, v221 row_shr:2 row_mask:0xf bank_mask:0xf
	v_fmac_f32_dpp v226, v226, v222 row_shr:2 row_mask:0xf bank_mask:0xf
	v_fmac_f32_dpp v227, v227, v223 row_shr:2 row_mask:0xf bank_mask:0xf
	v_fmac_f32_dpp v228, v228, v224 row_shr:2 row_mask:0xf bank_mask:0xf
	v_mul_f32_dpp v221, v221, v221 row_shr:2 row_mask:0xf bank_mask:0xf
	v_mul_f32_dpp v222, v222, v222 row_shr:2 row_mask:0xf bank_mask:0xf
	v_mul_f32_dpp v223, v223, v223 row_shr:2 row_mask:0xf bank_mask:0xf
	v_mul_f32_dpp v224, v224, v224 row_shr:2 row_mask:0xf bank_mask:0xf
	v_fmac_f32_dpp v225, v225, v221 row_shr:4 row_mask:0xf bank_mask:0xf
	v_fmac_f32_dpp v226, v226, v222 row_shr:4 row_mask:0xf bank_mask:0xf
	v_fmac_f32_dpp v227, v227, v223 row_shr:4 row_mask:0xf bank_mask:0xf
	v_fmac_f32_dpp v228, v228, v224 row_shr:4 row_mask:0xf bank_mask:0xf
	v_mul_f32_dpp v221, v221, v221 row_shr:4 row_mask:0xf bank_mask:0xf
	v_mul_f32_dpp v222, v222, v222 row_shr:4 row_mask:0xf bank_mask:0xf
	v_mul_f32_dpp v223, v223, v223 row_shr:4 row_mask:0xf bank_mask:0xf
	v_mul_f32_dpp v224, v224, v224 row_shr:4 row_mask:0xf bank_mask:0xf
	v_fmac_f32_dpp v225, v225, v221 row_shr:8 row_mask:0xf bank_mask:0xf
	v_fmac_f32_dpp v226, v226, v222 row_shr:8 row_mask:0xf bank_mask:0xf
	v_fmac_f32_dpp v227, v227, v223 row_shr:8 row_mask:0xf bank_mask:0xf
	v_fmac_f32_dpp v228, v228, v224 row_shr:8 row_mask:0xf bank_mask:0xf
	v_mul_f32_dpp v221, v221, v221 row_shr:8 row_mask:0xf bank_mask:0xf
	v_mul_f32_dpp v222, v222, v222 row_shr:8 row_mask:0xf bank_mask:0xf
	v_mul_f32_dpp v223, v223, v223 row_shr:8 row_mask:0xf bank_mask:0xf
	v_mul_f32_dpp v224, v224, v224 row_shr:8 row_mask:0xf bank_mask:0xf
	v_fma_f32 v242, v242, v221, v225
	v_fma_f32 v243, v243, v222, v226
	v_fma_f32 v244, v244, v223, v227
	v_fma_f32 v245, v245, v224, v228
	v_mul_f32_e32 v238, v238, v221
	v_mul_f32_e32 v239, v239, v222
	v_mul_f32_e32 v240, v240, v223
	v_mul_f32_e32 v241, v241, v224
	v_pk_mul_f32 v[120:121], v[120:121], v[136:137]
	v_lshlrev_b32_e32 v140, 16, v173
	v_lshlrev_b32_e32 v134, 16, v172
	v_and_b32_e32 v135, 0xffff0000, v172
	v_lshlrev_b64 v[132:133], 13, v[208:209]
	v_and_b32_e32 v141, 0xffff0000, v173
	v_pk_mul_f32 v[122:123], v[122:123], v[138:139]
	v_pk_mul_f32 v[120:121], v[120:121], v[134:135]
	v_pk_mul_f32 v[122:123], v[122:123], v[140:141]
	v_cvt_pk_bf16_f32 v120, v124, v120
	v_cvt_pk_bf16_f32 v121, v125, v121
	v_lshl_add_u64 v[124:125], s[92:93], 0, v[132:133]
	v_pk_mul_f32 v[116:117], v[64:65], v[116:117]
	v_cvt_pk_bf16_f32 v122, v126, v122
	v_cvt_pk_bf16_f32 v123, v127, v123
	v_lshl_add_u64 v[124:125], v[124:125], 0, v[196:197]
	v_pk_add_f32 v[112:113], v[112:113], v[72:73]
	v_pk_mul_f32 v[118:119], v[66:67], v[118:119]
	v_pk_mul_f32 v[116:117], v[116:117], s[62:63] op_sel_hi:[1,0]
	v_pk_add_f32 v[104:105], v[104:105], v[100:101]
	global_store_dwordx4 v[124:125], v[120:123], off
	v_lshlrev_b32_e32 v221, 16, v120
	v_lshlrev_b32_e32 v222, 16, v121
	v_lshlrev_b32_e32 v223, 16, v122
	v_lshlrev_b32_e32 v224, 16, v123
	v_and_b32_e32 v225, 0xffff0000, v120
	v_and_b32_e32 v226, 0xffff0000, v121
	v_and_b32_e32 v227, 0xffff0000, v122
	v_and_b32_e32 v228, 0xffff0000, v123
	v_exp_f32_e32 v221, v221
	v_exp_f32_e32 v222, v222
	v_exp_f32_e32 v223, v223
	v_exp_f32_e32 v224, v224
	v_fmac_f32_dpp v225, v225, v221 row_shr:1 row_mask:0xf bank_mask:0xf
	v_fmac_f32_dpp v226, v226, v222 row_shr:1 row_mask:0xf bank_mask:0xf
	v_fmac_f32_dpp v227, v227, v223 row_shr:1 row_mask:0xf bank_mask:0xf
	v_fmac_f32_dpp v228, v228, v224 row_shr:1 row_mask:0xf bank_mask:0xf
	v_mul_f32_dpp v221, v221, v221 row_shr:1 row_mask:0xf bank_mask:0xf
	v_mul_f32_dpp v222, v222, v222 row_shr:1 row_mask:0xf bank_mask:0xf
; __device__ __forceinline__ unsigned cvt_pk_bf16(float lo, float hi) { unsigned r; asm volatile("v_cvt_pk_bf16_f32 %0, %1, %2" : "=v"(r) : "v"(lo), "v"(hi)); return r; }
; __device__ __forceinline__ float bf_lo(unsigned w) { return __uint_as_float(w << 16); }
; __device__ __forceinline__ float bf_hi(unsigned w) { return __uint_as_float(w & 0xffff0000u); }
;     __device__ __forceinline__ void operator()(EPI_ARGS) const {
;     ...
;                     const unsigned w0 = n ? vv[ai][m].z : vv[ai][m].x, w1 = n ? vv[ai][m].w : vv[ai][m].y;
;                     const f32x4 vx = (f32x4){bf_lo(w0), bf_hi(w0), bf_lo(w1), bf_hi(w1)};
;                     const f32x4 r = sigmoid4(acc[ai][0][m][n] + ba[n]), ig = sigmoid4(acc[ai][1][m][n] + bi[n]);
;                     const f32x4 la = sp[n] * r * (-1.4426950409f);
;                     f32x4 av;
; #pragma unroll
;                     for (int j = 0; j < 4; ++j) av[j] = __builtin_amdgcn_exp2f(la[j]);
;                     const f32x4 om = 1.0f - av * av; f32x4 sq;
; #pragma unroll
;                     for (int j = 0; j < 4; ++j) sq[j] = __builtin_amdgcn_sqrtf(om[j]);
;                     const f32x4 bx = sq * ig * vx;
;                     u32x4 w; w.x = cvt_pk_bf16(la[0], bx[0]); w.y = cvt_pk_bf16(la[1], bx[1]); w.z = cvt_pk_bf16(la[2], bx[2]); w.w = cvt_pk_bf16(la[3], bx[3]);
;                     *(u32x4*)(AB + (size_t)row * LW + c0 + 4 * n) = w;
; __global__ void __launch_bounds__(NTHR, 2) hybrid_block_fwd(Args a) {
;     ...
;         for (int i = 0; i < CH_L; ++i) { const u32x2 q = pab[(size_t)i * (LW / 2)];
;             const f32x2 av = (f32x2){__builtin_amdgcn_exp2f(bf_lo(q.x)), __builtin_amdgcn_exp2f(bf_lo(q.y))}, bv = (f32x2){bf_hi(q.x), bf_hi(q.y)}; P = P * av; H = av * H + bv; }
	v_mul_f32_dpp v223, v223, v223 row_shr:1 row_mask:0xf bank_mask:0xf
	v_mul_f32_dpp v224, v224, v224 row_shr:1 row_mask:0xf bank_mask:0xf
	v_fmac_f32_dpp v225, v225, v221 row_shr:2 row_mask:0xf bank_mask:0xf
	v_fmac_f32_dpp v226, v226, v222 row_shr:2 row_mask:0xf bank_mask:0xf
	v_fmac_f32_dpp v227, v227, v223 row_shr:2 row_mask:0xf bank_mask:0xf
	v_fmac_f32_dpp v228, v228, v224 row_shr:2 row_mask:0xf bank_mask:0xf
	v_mul_f32_dpp v221, v221, v221 row_shr:2 row_mask:0xf bank_mask:0xf
	v_mul_f32_dpp v222, v222, v222 row_shr:2 row_mask:0xf bank_mask:0xf
	v_mul_f32_dpp v223, v223, v223 row_shr:2 row_mask:0xf bank_mask:0xf
	v_mul_f32_dpp v224, v224, v224 row_shr:2 row_mask:0xf bank_mask:0xf
	v_fmac_f32_dpp v225, v225, v221 row_shr:4 row_mask:0xf bank_mask:0xf
	v_fmac_f32_dpp v226, v226, v222 row_shr:4 row_mask:0xf bank_mask:0xf
	v_fmac_f32_dpp v227, v227, v223 row_shr:4 row_mask:0xf bank_mask:0xf
	v_fmac_f32_dpp v228, v228, v224 row_shr:4 row_mask:0xf bank_mask:0xf
	v_mul_f32_dpp v221, v221, v221 row_shr:4 row_mask:0xf bank_mask:0xf
	v_mul_f32_dpp v222, v222, v222 row_shr:4 row_mask:0xf bank_mask:0xf
	v_mul_f32_dpp v223, v223, v223 row_shr:4 row_mask:0xf bank_mask:0xf
	v_mul_f32_dpp v224, v224, v224 row_shr:4 row_mask:0xf bank_mask:0xf
	v_fmac_f32_dpp v225, v225, v221 row_shr:8 row_mask:0xf bank_mask:0xf
	v_fmac_f32_dpp v226, v226, v222 row_shr:8 row_mask:0xf bank_mask:0xf
	v_fmac_f32_dpp v227, v227, v223 row_shr:8 row_mask:0xf bank_mask:0xf
	v_fmac_f32_dpp v228, v228, v224 row_shr:8 row_mask:0xf bank_mask:0xf
	v_mul_f32_dpp v221, v221, v221 row_shr:8 row_mask:0xf bank_mask:0xf
	v_mul_f32_dpp v222, v222, v222 row_shr:8 row_mask:0xf bank_mask:0xf
	v_mul_f32_dpp v223, v223, v223 row_shr:8 row_mask:0xf bank_mask:0xf
	v_mul_f32_dpp v224, v224, v224 row_shr:8 row_mask:0xf bank_mask:0xf
	v_fma_f32 v234, v234, v221, v225
	v_fma_f32 v235, v235, v222, v226
	v_fma_f32 v236, v236, v223, v227
	v_fma_f32 v237, v237, v224, v228
	v_mul_f32_e32 v230, v230, v221
	v_mul_f32_e32 v231, v231, v222
	v_mul_f32_e32 v232, v232, v223
	v_mul_f32_e32 v233, v233, v224
	v_pk_add_f32 v[114:115], v[114:115], v[74:75]
	v_mul_f32_e32 v112, 0xbfb8aa3b, v112
	v_mul_f32_e32 v113, 0xbfb8aa3b, v113
	v_pk_mul_f32 v[118:119], v[118:119], s[62:63] op_sel_hi:[1,0]
	v_exp_f32_e32 v122, v116
	v_exp_f32_e32 v123, v117
	v_pk_add_f32 v[106:107], v[106:107], v[102:103]
	v_mul_f32_e32 v104, 0xbfb8aa3b, v104
	v_mul_f32_e32 v105, 0xbfb8aa3b, v105
	v_exp_f32_e32 v112, v112
	v_exp_f32_e32 v113, v113
	v_mul_f32_e32 v114, 0xbfb8aa3b, v114
	v_mul_f32_e32 v115, 0xbfb8aa3b, v115
	v_exp_f32_e32 v126, v118
	v_exp_f32_e32 v127, v119
	v_exp_f32_e32 v104, v104
	v_exp_f32_e32 v105, v105
	v_mul_f32_e32 v106, 0xbfb8aa3b, v106
	v_mul_f32_e32 v107, 0xbfb8aa3b, v107
	v_exp_f32_e32 v114, v114
	v_exp_f32_e32 v115, v115
	v_exp_f32_e32 v106, v106
	v_exp_f32_e32 v107, v107
	v_pk_mul_f32 v[122:123], v[122:123], v[122:123]
	v_add_f32_e32 v112, 1.0, v112
	v_add_f32_e32 v113, 1.0, v113
	v_pk_mul_f32 v[126:127], v[126:127], v[126:127]
	v_sub_f32_e32 v122, 1.0, v122
	v_sub_f32_e32 v123, 1.0, v123
	v_add_f32_e32 v104, 1.0, v104
	v_add_f32_e32 v105, 1.0, v105
	v_rcp_f32_e32 v112, v112
	v_rcp_f32_e32 v113, v113
	v_add_f32_e32 v114, 1.0, v114
	v_add_f32_e32 v115, 1.0, v115
	v_sqrt_f32_e32 v122, v122
	v_sub_f32_e32 v126, 1.0, v126
	v_sub_f32_e32 v127, 1.0, v127
	v_sqrt_f32_e32 v123, v123
	v_rcp_f32_e32 v104, v104
	v_rcp_f32_e32 v105, v105
	v_add_f32_e32 v106, 1.0, v106
	v_add_f32_e32 v107, 1.0, v107
	v_rcp_f32_e32 v114, v114
	v_rcp_f32_e32 v115, v115
	v_sqrt_f32_e32 v126, v126
	v_sqrt_f32_e32 v127, v127
	v_rcp_f32_e32 v106, v106
	v_rcp_f32_e32 v107, v107
	v_lshlrev_b32_e32 v120, 16, v174
	v_and_b32_e32 v121, 0xffff0000, v174
	v_pk_mul_f32 v[112:113], v[112:113], v[122:123]
	v_pk_mul_f32 v[104:105], v[88:89], v[104:105]
	v_lshlrev_b32_e32 v132, 16, v175
	v_and_b32_e32 v133, 0xffff0000, v175
	v_pk_mul_f32 v[114:115], v[114:115], v[126:127]
	v_pk_mul_f32 v[112:113], v[112:113], v[120:121]
	v_pk_add_f32 v[96:97], v[96:97], v[92:93]
	v_pk_mul_f32 v[106:107], v[90:91], v[106:107]
	v_pk_mul_f32 v[104:105], v[104:105], s[62:63] op_sel_hi:[1,0]
	v_pk_mul_f32 v[114:115], v[114:115], v[132:133]
	v_cvt_pk_bf16_f32 v112, v116, v112
	v_cvt_pk_bf16_f32 v113, v117, v113
	v_pk_add_f32 v[98:99], v[98:99], v[94:95]
	v_mul_f32_e32 v96, 0xbfb8aa3b, v96
	v_mul_f32_e32 v97, 0xbfb8aa3b, v97
	v_pk_mul_f32 v[106:107], v[106:107], s[62:63] op_sel_hi:[1,0]
	v_exp_f32_e32 v116, v104
	v_exp_f32_e32 v117, v105
	v_cvt_pk_bf16_f32 v114, v118, v114
	v_cvt_pk_bf16_f32 v115, v119, v115
	v_exp_f32_e32 v96, v96
	v_exp_f32_e32 v97, v97
	v_mul_f32_e32 v98, 0xbfb8aa3b, v98
	v_mul_f32_e32 v99, 0xbfb8aa3b, v99
	v_exp_f32_e32 v118, v106
	v_exp_f32_e32 v119, v107
	v_pk_add_f32 v[84:85], v[84:85], v[80:81]
	v_exp_f32_e32 v98, v98
	v_exp_f32_e32 v99, v99
	v_pk_add_f32 v[86:87], v[86:87], v[82:83]
	v_mul_f32_e32 v84, 0xbfb8aa3b, v84
	v_mul_f32_e32 v85, 0xbfb8aa3b, v85
	v_exp_f32_e32 v84, v84
	v_exp_f32_e32 v85, v85
	v_mul_f32_e32 v86, 0xbfb8aa3b, v86
	v_mul_f32_e32 v87, 0xbfb8aa3b, v87
	v_pk_mul_f32 v[116:117], v[116:117], v[116:117]
	v_exp_f32_e32 v86, v86
	v_exp_f32_e32 v87, v87
	v_add_f32_e32 v96, 1.0, v96
	v_add_f32_e32 v97, 1.0, v97
	v_pk_mul_f32 v[118:119], v[118:119], v[118:119]
	v_sub_f32_e32 v116, 1.0, v116
	v_sub_f32_e32 v117, 1.0, v117
	v_rcp_f32_e32 v96, v96
	v_rcp_f32_e32 v97, v97
	v_add_f32_e32 v98, 1.0, v98
	v_add_f32_e32 v99, 1.0, v99
	v_sqrt_f32_e32 v116, v116
	v_sub_f32_e32 v118, 1.0, v118
	v_sub_f32_e32 v119, 1.0, v119
	v_sqrt_f32_e32 v117, v117
	v_rcp_f32_e32 v98, v98
	v_rcp_f32_e32 v99, v99
	v_sqrt_f32_e32 v118, v118
	v_sqrt_f32_e32 v119, v119
; __device__ __forceinline__ unsigned cvt_pk_bf16(float lo, float hi) { unsigned r; asm volatile("v_cvt_pk_bf16_f32 %0, %1, %2" : "=v"(r) : "v"(lo), "v"(hi)); return r; }
; __device__ __forceinline__ float bf_lo(unsigned w) { return __uint_as_float(w << 16); }
; __device__ __forceinline__ float bf_hi(unsigned w) { return __uint_as_float(w & 0xffff0000u); }
;     __device__ __forceinline__ void operator()(EPI_ARGS) const {
;     ...
;                     const unsigned w0 = n ? vv[ai][m].z : vv[ai][m].x, w1 = n ? vv[ai][m].w : vv[ai][m].y;
;                     const f32x4 vx = (f32x4){bf_lo(w0), bf_hi(w0), bf_lo(w1), bf_hi(w1)};
;                     const f32x4 r = sigmoid4(acc[ai][0][m][n] + ba[n]), ig = sigmoid4(acc[ai][1][m][n] + bi[n]);
;                     const f32x4 la = sp[n] * r * (-1.4426950409f);
;                     f32x4 av;
; #pragma unroll
;                     for (int j = 0; j < 4; ++j) av[j] = __builtin_amdgcn_exp2f(la[j]);
;                     const f32x4 om = 1.0f - av * av; f32x4 sq;
; #pragma unroll
;                     for (int j = 0; j < 4; ++j) sq[j] = __builtin_amdgcn_sqrtf(om[j]);
;                     const f32x4 bx = sq * ig * vx;
;                     u32x4 w; w.x = cvt_pk_bf16(la[0], bx[0]); w.y = cvt_pk_bf16(la[1], bx[1]); w.z = cvt_pk_bf16(la[2], bx[2]); w.w = cvt_pk_bf16(la[3], bx[3]);
;                     *(u32x4*)(AB + (size_t)row * LW + c0 + 4 * n) = w;
; __global__ void __launch_bounds__(NTHR, 2) hybrid_block_fwd(Args a) {
;     ...
;         for (int i = 0; i < CH_L; ++i) { const u32x2 q = pab[(size_t)i * (LW / 2)];
;             const f32x2 av = (f32x2){__builtin_amdgcn_exp2f(bf_lo(q.x)), __builtin_amdgcn_exp2f(bf_lo(q.y))}, bv = (f32x2){bf_hi(q.x), bf_hi(q.y)}; P = P * av; H = av * H + bv; }
	v_add_f32_e32 v84, 1.0, v84
	v_add_f32_e32 v85, 1.0, v85
	v_rcp_f32_e32 v84, v84
	v_rcp_f32_e32 v85, v85
	v_add_f32_e32 v86, 1.0, v86
	v_add_f32_e32 v87, 1.0, v87
	v_rcp_f32_e32 v86, v86
	v_rcp_f32_e32 v87, v87
	global_store_dwordx4 v[124:125], v[112:115], off offset:16
	v_lshlrev_b32_e32 v221, 16, v112
	v_lshlrev_b32_e32 v222, 16, v113
	v_lshlrev_b32_e32 v223, 16, v114
	v_lshlrev_b32_e32 v224, 16, v115
	v_and_b32_e32 v225, 0xffff0000, v112
	v_and_b32_e32 v226, 0xffff0000, v113
	v_and_b32_e32 v227, 0xffff0000, v114
	v_and_b32_e32 v228, 0xffff0000, v115
	v_exp_f32_e32 v221, v221
	v_exp_f32_e32 v222, v222
	v_exp_f32_e32 v223, v223
	v_exp_f32_e32 v224, v224
	v_fmac_f32_dpp v225, v225, v221 row_shr:1 row_mask:0xf bank_mask:0xf
	v_fmac_f32_dpp v226, v226, v222 row_shr:1 row_mask:0xf bank_mask:0xf
	v_fmac_f32_dpp v227, v227, v223 row_shr:1 row_mask:0xf bank_mask:0xf
	v_fmac_f32_dpp v228, v228, v224 row_shr:1 row_mask:0xf bank_mask:0xf
	v_mul_f32_dpp v221, v221, v221 row_shr:1 row_mask:0xf bank_mask:0xf
	v_mul_f32_dpp v222, v222, v222 row_shr:1 row_mask:0xf bank_mask:0xf
	v_mul_f32_dpp v223, v223, v223 row_shr:1 row_mask:0xf bank_mask:0xf
	v_mul_f32_dpp v224, v224, v224 row_shr:1 row_mask:0xf bank_mask:0xf
	v_fmac_f32_dpp v225, v225, v221 row_shr:2 row_mask:0xf bank_mask:0xf
	v_fmac_f32_dpp v226, v226, v222 row_shr:2 row_mask:0xf bank_mask:0xf
	v_fmac_f32_dpp v227, v227, v223 row_shr:2 row_mask:0xf bank_mask:0xf
	v_fmac_f32_dpp v228, v228, v224 row_shr:2 row_mask:0xf bank_mask:0xf
	v_mul_f32_dpp v221, v221, v221 row_shr:2 row_mask:0xf bank_mask:0xf
	v_mul_f32_dpp v222, v222, v222 row_shr:2 row_mask:0xf bank_mask:0xf
	v_mul_f32_dpp v223, v223, v223 row_shr:2 row_mask:0xf bank_mask:0xf
	v_mul_f32_dpp v224, v224, v224 row_shr:2 row_mask:0xf bank_mask:0xf
	v_fmac_f32_dpp v225, v225, v221 row_shr:4 row_mask:0xf bank_mask:0xf
	v_fmac_f32_dpp v226, v226, v222 row_shr:4 row_mask:0xf bank_mask:0xf
	v_fmac_f32_dpp v227, v227, v223 row_shr:4 row_mask:0xf bank_mask:0xf
	v_fmac_f32_dpp v228, v228, v224 row_shr:4 row_mask:0xf bank_mask:0xf
	v_mul_f32_dpp v221, v221, v221 row_shr:4 row_mask:0xf bank_mask:0xf
	v_mul_f32_dpp v222, v222, v222 row_shr:4 row_mask:0xf bank_mask:0xf
	v_mul_f32_dpp v223, v223, v223 row_shr:4 row_mask:0xf bank_mask:0xf
	v_mul_f32_dpp v224, v224, v224 row_shr:4 row_mask:0xf bank_mask:0xf
	v_fmac_f32_dpp v225, v225, v221 row_shr:8 row_mask:0xf bank_mask:0xf
	v_fmac_f32_dpp v226, v226, v222 row_shr:8 row_mask:0xf bank_mask:0xf
	v_fmac_f32_dpp v227, v227, v223 row_shr:8 row_mask:0xf bank_mask:0xf
	v_fmac_f32_dpp v228, v228, v224 row_shr:8 row_mask:0xf bank_mask:0xf
	v_mul_f32_dpp v221, v221, v221 row_shr:8 row_mask:0xf bank_mask:0xf
	v_mul_f32_dpp v222, v222, v222 row_shr:8 row_mask:0xf bank_mask:0xf
	v_mul_f32_dpp v223, v223, v223 row_shr:8 row_mask:0xf bank_mask:0xf
	v_mul_f32_dpp v224, v224, v224 row_shr:8 row_mask:0xf bank_mask:0xf
	v_fma_f32 v242, v242, v221, v225
	v_fma_f32 v243, v243, v222, v226
	v_fma_f32 v244, v244, v223, v227
	v_fma_f32 v245, v245, v224, v228
	v_mul_f32_e32 v238, v238, v221
	v_mul_f32_e32 v239, v239, v222
	v_mul_f32_e32 v240, v240, v223
	v_mul_f32_e32 v241, v241, v224
	v_pk_mul_f32 v[96:97], v[96:97], v[116:117]
	v_lshlrev_b32_e32 v120, 16, v165
	v_lshlrev_b32_e32 v114, 16, v164
	v_and_b32_e32 v115, 0xffff0000, v164
	v_lshlrev_b64 v[112:113], 13, v[206:207]
	v_and_b32_e32 v121, 0xffff0000, v165
	v_pk_mul_f32 v[98:99], v[98:99], v[118:119]
	v_pk_mul_f32 v[96:97], v[96:97], v[114:115]
	v_pk_mul_f32 v[98:99], v[98:99], v[120:121]
	v_cvt_pk_bf16_f32 v96, v104, v96
	v_cvt_pk_bf16_f32 v97, v105, v97
	v_lshl_add_u64 v[104:105], s[92:93], 0, v[112:113]
	v_pk_mul_f32 v[84:85], v[64:65], v[84:85]
	v_cvt_pk_bf16_f32 v98, v106, v98
	v_cvt_pk_bf16_f32 v99, v107, v99
	v_lshl_add_u64 v[104:105], v[104:105], 0, v[196:197]
	v_pk_add_f32 v[76:77], v[76:77], v[72:73]
	v_pk_mul_f32 v[86:87], v[66:67], v[86:87]
	v_pk_mul_f32 v[84:85], v[84:85], s[62:63] op_sel_hi:[1,0]
	v_pk_add_f32 v[60:61], v[60:61], v[100:101]
	global_store_dwordx4 v[104:105], v[96:99], off
	v_lshlrev_b32_e32 v221, 16, v96
	v_lshlrev_b32_e32 v222, 16, v97
	v_lshlrev_b32_e32 v223, 16, v98
	v_lshlrev_b32_e32 v224, 16, v99
	v_and_b32_e32 v225, 0xffff0000, v96
	v_and_b32_e32 v226, 0xffff0000, v97
	v_and_b32_e32 v227, 0xffff0000, v98
	v_and_b32_e32 v228, 0xffff0000, v99
	v_exp_f32_e32 v221, v221
	v_exp_f32_e32 v222, v222
	v_exp_f32_e32 v223, v223
	v_exp_f32_e32 v224, v224
	v_fmac_f32_dpp v225, v225, v221 row_shr:1 row_mask:0xf bank_mask:0xf
	v_fmac_f32_dpp v226, v226, v222 row_shr:1 row_mask:0xf bank_mask:0xf
	v_fmac_f32_dpp v227, v227, v223 row_shr:1 row_mask:0xf bank_mask:0xf
	v_fmac_f32_dpp v228, v228, v224 row_shr:1 row_mask:0xf bank_mask:0xf
	v_mul_f32_dpp v221, v221, v221 row_shr:1 row_mask:0xf bank_mask:0xf
	v_mul_f32_dpp v222, v222, v222 row_shr:1 row_mask:0xf bank_mask:0xf
	v_mul_f32_dpp v223, v223, v223 row_shr:1 row_mask:0xf bank_mask:0xf
	v_mul_f32_dpp v224, v224, v224 row_shr:1 row_mask:0xf bank_mask:0xf
	v_fmac_f32_dpp v225, v225, v221 row_shr:2 row_mask:0xf bank_mask:0xf
	v_fmac_f32_dpp v226, v226, v222 row_shr:2 row_mask:0xf bank_mask:0xf
	v_fmac_f32_dpp v227, v227, v223 row_shr:2 row_mask:0xf bank_mask:0xf
	v_fmac_f32_dpp v228, v228, v224 row_shr:2 row_mask:0xf bank_mask:0xf
	v_mul_f32_dpp v221, v221, v221 row_shr:2 row_mask:0xf bank_mask:0xf
	v_mul_f32_dpp v222, v222, v222 row_shr:2 row_mask:0xf bank_mask:0xf
	v_mul_f32_dpp v223, v223, v223 row_shr:2 row_mask:0xf bank_mask:0xf
	v_mul_f32_dpp v224, v224, v224 row_shr:2 row_mask:0xf bank_mask:0xf
	v_fmac_f32_dpp v225, v225, v221 row_shr:4 row_mask:0xf bank_mask:0xf
; __device__ __forceinline__ unsigned cvt_pk_bf16(float lo, float hi) { unsigned r; asm volatile("v_cvt_pk_bf16_f32 %0, %1, %2" : "=v"(r) : "v"(lo), "v"(hi)); return r; }
; __device__ __forceinline__ float bf_lo(unsigned w) { return __uint_as_float(w << 16); }
; __device__ __forceinline__ float bf_hi(unsigned w) { return __uint_as_float(w & 0xffff0000u); }
;     __device__ __forceinline__ void operator()(EPI_ARGS) const {
;     ...
;                     const unsigned w0 = n ? vv[ai][m].z : vv[ai][m].x, w1 = n ? vv[ai][m].w : vv[ai][m].y;
;                     const f32x4 vx = (f32x4){bf_lo(w0), bf_hi(w0), bf_lo(w1), bf_hi(w1)};
;                     const f32x4 r = sigmoid4(acc[ai][0][m][n] + ba[n]), ig = sigmoid4(acc[ai][1][m][n] + bi[n]);
;                     const f32x4 la = sp[n] * r * (-1.4426950409f);
;                     f32x4 av;
; #pragma unroll
;                     for (int j = 0; j < 4; ++j) av[j] = __builtin_amdgcn_exp2f(la[j]);
;                     const f32x4 om = 1.0f - av * av; f32x4 sq;
; #pragma unroll
;                     for (int j = 0; j < 4; ++j) sq[j] = __builtin_amdgcn_sqrtf(om[j]);
;                     const f32x4 bx = sq * ig * vx;
;                     u32x4 w; w.x = cvt_pk_bf16(la[0], bx[0]); w.y = cvt_pk_bf16(la[1], bx[1]); w.z = cvt_pk_bf16(la[2], bx[2]); w.w = cvt_pk_bf16(la[3], bx[3]);
;                     *(u32x4*)(AB + (size_t)row * LW + c0 + 4 * n) = w;
; __global__ void __launch_bounds__(NTHR, 2) hybrid_block_fwd(Args a) {
;     ...
;         for (int i = 0; i < CH_L; ++i) { const u32x2 q = pab[(size_t)i * (LW / 2)];
;             const f32x2 av = (f32x2){__builtin_amdgcn_exp2f(bf_lo(q.x)), __builtin_amdgcn_exp2f(bf_lo(q.y))}, bv = (f32x2){bf_hi(q.x), bf_hi(q.y)}; P = P * av; H = av * H + bv; }
	v_fmac_f32_dpp v226, v226, v222 row_shr:4 row_mask:0xf bank_mask:0xf
	v_fmac_f32_dpp v227, v227, v223 row_shr:4 row_mask:0xf bank_mask:0xf
	v_fmac_f32_dpp v228, v228, v224 row_shr:4 row_mask:0xf bank_mask:0xf
	v_mul_f32_dpp v221, v221, v221 row_shr:4 row_mask:0xf bank_mask:0xf
	v_mul_f32_dpp v222, v222, v222 row_shr:4 row_mask:0xf bank_mask:0xf
	v_mul_f32_dpp v223, v223, v223 row_shr:4 row_mask:0xf bank_mask:0xf
	v_mul_f32_dpp v224, v224, v224 row_shr:4 row_mask:0xf bank_mask:0xf
	v_fmac_f32_dpp v225, v225, v221 row_shr:8 row_mask:0xf bank_mask:0xf
	v_fmac_f32_dpp v226, v226, v222 row_shr:8 row_mask:0xf bank_mask:0xf
	v_fmac_f32_dpp v227, v227, v223 row_shr:8 row_mask:0xf bank_mask:0xf
	v_fmac_f32_dpp v228, v228, v224 row_shr:8 row_mask:0xf bank_mask:0xf
	v_mul_f32_dpp v221, v221, v221 row_shr:8 row_mask:0xf bank_mask:0xf
	v_mul_f32_dpp v222, v222, v222 row_shr:8 row_mask:0xf bank_mask:0xf
	v_mul_f32_dpp v223, v223, v223 row_shr:8 row_mask:0xf bank_mask:0xf
	v_mul_f32_dpp v224, v224, v224 row_shr:8 row_mask:0xf bank_mask:0xf
	v_fma_f32 v234, v234, v221, v225
	v_fma_f32 v235, v235, v222, v226
	v_fma_f32 v236, v236, v223, v227
	v_fma_f32 v237, v237, v224, v228
	v_mul_f32_e32 v230, v230, v221
	v_mul_f32_e32 v231, v231, v222
	v_mul_f32_e32 v232, v232, v223
	v_mul_f32_e32 v233, v233, v224
	v_pk_add_f32 v[78:79], v[78:79], v[74:75]
	v_mul_f32_e32 v76, 0xbfb8aa3b, v76
	v_mul_f32_e32 v77, 0xbfb8aa3b, v77
	v_pk_mul_f32 v[86:87], v[86:87], s[62:63] op_sel_hi:[1,0]
	v_exp_f32_e32 v98, v84
	v_exp_f32_e32 v99, v85
	v_pk_add_f32 v[62:63], v[62:63], v[102:103]
	v_mul_f32_e32 v60, 0xbfb8aa3b, v60
	v_mul_f32_e32 v61, 0xbfb8aa3b, v61
	v_exp_f32_e32 v76, v76
	v_exp_f32_e32 v77, v77
	v_mul_f32_e32 v78, 0xbfb8aa3b, v78
	v_mul_f32_e32 v79, 0xbfb8aa3b, v79
	v_exp_f32_e32 v106, v86
	v_exp_f32_e32 v107, v87
	v_exp_f32_e32 v60, v60
	v_exp_f32_e32 v61, v61
	v_mul_f32_e32 v62, 0xbfb8aa3b, v62
	v_mul_f32_e32 v63, 0xbfb8aa3b, v63
	v_exp_f32_e32 v78, v78
	v_exp_f32_e32 v79, v79
	v_exp_f32_e32 v62, v62
	v_exp_f32_e32 v63, v63
	v_pk_mul_f32 v[98:99], v[98:99], v[98:99]
	v_add_f32_e32 v76, 1.0, v76
	v_add_f32_e32 v77, 1.0, v77
	v_pk_mul_f32 v[106:107], v[106:107], v[106:107]
	v_sub_f32_e32 v98, 1.0, v98
	v_sub_f32_e32 v99, 1.0, v99
	v_add_f32_e32 v60, 1.0, v60
	v_add_f32_e32 v61, 1.0, v61
	v_rcp_f32_e32 v76, v76
	v_rcp_f32_e32 v77, v77
	v_add_f32_e32 v78, 1.0, v78
	v_add_f32_e32 v79, 1.0, v79
	v_sqrt_f32_e32 v98, v98
	v_sub_f32_e32 v106, 1.0, v106
	v_sub_f32_e32 v107, 1.0, v107
	v_sqrt_f32_e32 v99, v99
	v_rcp_f32_e32 v60, v60
	v_rcp_f32_e32 v61, v61
	v_add_f32_e32 v62, 1.0, v62
	v_add_f32_e32 v63, 1.0, v63
	v_rcp_f32_e32 v78, v78
	v_rcp_f32_e32 v79, v79
	v_sqrt_f32_e32 v106, v106
	v_sqrt_f32_e32 v107, v107
	v_rcp_f32_e32 v62, v62
	v_rcp_f32_e32 v63, v63
	v_lshlrev_b32_e32 v96, 16, v166
	v_and_b32_e32 v97, 0xffff0000, v166
	v_pk_mul_f32 v[76:77], v[76:77], v[98:99]
	v_pk_mul_f32 v[60:61], v[88:89], v[60:61]
	v_lshlrev_b32_e32 v112, 16, v167
	v_and_b32_e32 v113, 0xffff0000, v167
	v_pk_mul_f32 v[78:79], v[78:79], v[106:107]
	v_pk_mul_f32 v[76:77], v[76:77], v[96:97]
	v_pk_add_f32 v[56:57], v[56:57], v[92:93]
	v_pk_mul_f32 v[62:63], v[90:91], v[62:63]
	v_pk_mul_f32 v[60:61], v[60:61], s[62:63] op_sel_hi:[1,0]
	v_pk_mul_f32 v[78:79], v[78:79], v[112:113]
	v_cvt_pk_bf16_f32 v76, v84, v76
	v_cvt_pk_bf16_f32 v77, v85, v77
	v_pk_add_f32 v[58:59], v[58:59], v[94:95]
	v_mul_f32_e32 v56, 0xbfb8aa3b, v56
	v_mul_f32_e32 v57, 0xbfb8aa3b, v57
	v_pk_mul_f32 v[62:63], v[62:63], s[62:63] op_sel_hi:[1,0]
	v_exp_f32_e32 v84, v60
	v_exp_f32_e32 v85, v61
	v_cvt_pk_bf16_f32 v78, v86, v78
	v_cvt_pk_bf16_f32 v79, v87, v79
	v_exp_f32_e32 v56, v56
	v_exp_f32_e32 v57, v57
	v_mul_f32_e32 v58, 0xbfb8aa3b, v58
	v_mul_f32_e32 v59, 0xbfb8aa3b, v59
	v_exp_f32_e32 v86, v62
	v_exp_f32_e32 v87, v63
	v_pk_add_f32 v[52:53], v[52:53], v[80:81]
	v_exp_f32_e32 v58, v58
	v_exp_f32_e32 v59, v59
	v_pk_add_f32 v[54:55], v[54:55], v[82:83]
	v_mul_f32_e32 v52, 0xbfb8aa3b, v52
	v_mul_f32_e32 v53, 0xbfb8aa3b, v53
	v_exp_f32_e32 v52, v52
	v_exp_f32_e32 v53, v53
	v_mul_f32_e32 v54, 0xbfb8aa3b, v54
	v_mul_f32_e32 v55, 0xbfb8aa3b, v55
	v_pk_mul_f32 v[84:85], v[84:85], v[84:85]
	v_exp_f32_e32 v54, v54
	v_exp_f32_e32 v55, v55
	v_add_f32_e32 v56, 1.0, v56
	v_add_f32_e32 v57, 1.0, v57
	v_pk_mul_f32 v[86:87], v[86:87], v[86:87]
	v_sub_f32_e32 v84, 1.0, v84
	v_sub_f32_e32 v85, 1.0, v85
	v_rcp_f32_e32 v56, v56
	v_rcp_f32_e32 v57, v57
	v_add_f32_e32 v58, 1.0, v58
	v_add_f32_e32 v59, 1.0, v59
	v_sqrt_f32_e32 v84, v84
	v_sub_f32_e32 v86, 1.0, v86
	v_sub_f32_e32 v87, 1.0, v87
	v_sqrt_f32_e32 v85, v85
	v_rcp_f32_e32 v58, v58
	v_rcp_f32_e32 v59, v59
	v_sqrt_f32_e32 v86, v86
	v_sqrt_f32_e32 v87, v87
	v_add_f32_e32 v52, 1.0, v52
	v_add_f32_e32 v53, 1.0, v53
	v_rcp_f32_e32 v52, v52
	v_rcp_f32_e32 v53, v53
	v_add_f32_e32 v54, 1.0, v54
	v_add_f32_e32 v55, 1.0, v55
	v_rcp_f32_e32 v54, v54
	v_rcp_f32_e32 v55, v55
	global_store_dwordx4 v[104:105], v[76:79], off offset:16
	v_lshlrev_b32_e32 v221, 16, v76
	v_lshlrev_b32_e32 v222, 16, v77
	v_lshlrev_b32_e32 v223, 16, v78
	v_lshlrev_b32_e32 v224, 16, v79
	v_and_b32_e32 v225, 0xffff0000, v76
	v_and_b32_e32 v226, 0xffff0000, v77
	v_and_b32_e32 v227, 0xffff0000, v78
	v_and_b32_e32 v228, 0xffff0000, v79
	v_exp_f32_e32 v221, v221
	v_exp_f32_e32 v222, v222
	v_exp_f32_e32 v223, v223
	v_exp_f32_e32 v224, v224
	v_fmac_f32_dpp v225, v225, v221 row_shr:1 row_mask:0xf bank_mask:0xf
	v_fmac_f32_dpp v226, v226, v222 row_shr:1 row_mask:0xf bank_mask:0xf
	v_fmac_f32_dpp v227, v227, v223 row_shr:1 row_mask:0xf bank_mask:0xf
	v_fmac_f32_dpp v228, v228, v224 row_shr:1 row_mask:0xf bank_mask:0xf
; __device__ __forceinline__ unsigned cvt_pk_bf16(float lo, float hi) { unsigned r; asm volatile("v_cvt_pk_bf16_f32 %0, %1, %2" : "=v"(r) : "v"(lo), "v"(hi)); return r; }
; __device__ __forceinline__ float bf_lo(unsigned w) { return __uint_as_float(w << 16); }
; __device__ __forceinline__ float bf_hi(unsigned w) { return __uint_as_float(w & 0xffff0000u); }
;     __device__ __forceinline__ void operator()(EPI_ARGS) const {
;     ...
;                     const unsigned w0 = n ? vv[ai][m].z : vv[ai][m].x, w1 = n ? vv[ai][m].w : vv[ai][m].y;
;                     const f32x4 vx = (f32x4){bf_lo(w0), bf_hi(w0), bf_lo(w1), bf_hi(w1)};
;                     const f32x4 r = sigmoid4(acc[ai][0][m][n] + ba[n]), ig = sigmoid4(acc[ai][1][m][n] + bi[n]);
;                     const f32x4 la = sp[n] * r * (-1.4426950409f);
;                     f32x4 av;
; #pragma unroll
;                     for (int j = 0; j < 4; ++j) av[j] = __builtin_amdgcn_exp2f(la[j]);
;                     const f32x4 om = 1.0f - av * av; f32x4 sq;
; #pragma unroll
;                     for (int j = 0; j < 4; ++j) sq[j] = __builtin_amdgcn_sqrtf(om[j]);
;                     const f32x4 bx = sq * ig * vx;
;                     u32x4 w; w.x = cvt_pk_bf16(la[0], bx[0]); w.y = cvt_pk_bf16(la[1], bx[1]); w.z = cvt_pk_bf16(la[2], bx[2]); w.w = cvt_pk_bf16(la[3], bx[3]);
;                     *(u32x4*)(AB + (size_t)row * LW + c0 + 4 * n) = w;
; __global__ void __launch_bounds__(NTHR, 2) hybrid_block_fwd(Args a) {
;     ...
;         for (int i = 0; i < CH_L; ++i) { const u32x2 q = pab[(size_t)i * (LW / 2)];
;             const f32x2 av = (f32x2){__builtin_amdgcn_exp2f(bf_lo(q.x)), __builtin_amdgcn_exp2f(bf_lo(q.y))}, bv = (f32x2){bf_hi(q.x), bf_hi(q.y)}; P = P * av; H = av * H + bv; }
	v_mul_f32_dpp v221, v221, v221 row_shr:1 row_mask:0xf bank_mask:0xf
	v_mul_f32_dpp v222, v222, v222 row_shr:1 row_mask:0xf bank_mask:0xf
	v_mul_f32_dpp v223, v223, v223 row_shr:1 row_mask:0xf bank_mask:0xf
	v_mul_f32_dpp v224, v224, v224 row_shr:1 row_mask:0xf bank_mask:0xf
	v_fmac_f32_dpp v225, v225, v221 row_shr:2 row_mask:0xf bank_mask:0xf
	v_fmac_f32_dpp v226, v226, v222 row_shr:2 row_mask:0xf bank_mask:0xf
	v_fmac_f32_dpp v227, v227, v223 row_shr:2 row_mask:0xf bank_mask:0xf
	v_fmac_f32_dpp v228, v228, v224 row_shr:2 row_mask:0xf bank_mask:0xf
	v_mul_f32_dpp v221, v221, v221 row_shr:2 row_mask:0xf bank_mask:0xf
	v_mul_f32_dpp v222, v222, v222 row_shr:2 row_mask:0xf bank_mask:0xf
	v_mul_f32_dpp v223, v223, v223 row_shr:2 row_mask:0xf bank_mask:0xf
	v_mul_f32_dpp v224, v224, v224 row_shr:2 row_mask:0xf bank_mask:0xf
	v_fmac_f32_dpp v225, v225, v221 row_shr:4 row_mask:0xf bank_mask:0xf
	v_fmac_f32_dpp v226, v226, v222 row_shr:4 row_mask:0xf bank_mask:0xf
	v_fmac_f32_dpp v227, v227, v223 row_shr:4 row_mask:0xf bank_mask:0xf
	v_fmac_f32_dpp v228, v228, v224 row_shr:4 row_mask:0xf bank_mask:0xf
	v_mul_f32_dpp v221, v221, v221 row_shr:4 row_mask:0xf bank_mask:0xf
	v_mul_f32_dpp v222, v222, v222 row_shr:4 row_mask:0xf bank_mask:0xf
	v_mul_f32_dpp v223, v223, v223 row_shr:4 row_mask:0xf bank_mask:0xf
	v_mul_f32_dpp v224, v224, v224 row_shr:4 row_mask:0xf bank_mask:0xf
	v_fmac_f32_dpp v225, v225, v221 row_shr:8 row_mask:0xf bank_mask:0xf
	v_fmac_f32_dpp v226, v226, v222 row_shr:8 row_mask:0xf bank_mask:0xf
	v_fmac_f32_dpp v227, v227, v223 row_shr:8 row_mask:0xf bank_mask:0xf
	v_fmac_f32_dpp v228, v228, v224 row_shr:8 row_mask:0xf bank_mask:0xf
	v_mul_f32_dpp v221, v221, v221 row_shr:8 row_mask:0xf bank_mask:0xf
	v_mul_f32_dpp v222, v222, v222 row_shr:8 row_mask:0xf bank_mask:0xf
	v_mul_f32_dpp v223, v223, v223 row_shr:8 row_mask:0xf bank_mask:0xf
	v_mul_f32_dpp v224, v224, v224 row_shr:8 row_mask:0xf bank_mask:0xf
	v_fma_f32 v242, v242, v221, v225
	v_fma_f32 v243, v243, v222, v226
	v_fma_f32 v244, v244, v223, v227
	v_fma_f32 v245, v245, v224, v228
	v_mul_f32_e32 v238, v238, v221
	v_mul_f32_e32 v239, v239, v222
	v_mul_f32_e32 v240, v240, v223
	v_mul_f32_e32 v241, v241, v224
	v_mov_b32_e32 v152, v230
	v_mov_b32_e32 v153, v231
	v_mov_b32_e32 v154, v232
	v_mov_b32_e32 v155, v233
	v_mov_b32_e32 v156, v234
	v_mov_b32_e32 v157, v235
	v_mov_b32_e32 v158, v236
	v_mov_b32_e32 v159, v237
	v_mov_b32_e32 v160, v238
	v_mov_b32_e32 v161, v239
	v_mov_b32_e32 v162, v240
	v_mov_b32_e32 v163, v241
	v_mov_b32_e32 v164, v242
	v_mov_b32_e32 v165, v243
	v_mov_b32_e32 v166, v244
	v_mov_b32_e32 v167, v245
	v_pk_mul_f32 v[56:57], v[56:57], v[84:85]
	v_lshlrev_b32_e32 v96, 16, v149
	v_lshlrev_b32_e32 v78, 16, v148
	v_and_b32_e32 v79, 0xffff0000, v148
	v_lshlrev_b64 v[76:77], 13, v[204:205]
	v_and_b32_e32 v97, 0xffff0000, v149
	v_pk_mul_f32 v[58:59], v[58:59], v[86:87]
	v_pk_mul_f32 v[56:57], v[56:57], v[78:79]
	v_pk_mul_f32 v[58:59], v[58:59], v[96:97]
	v_cvt_pk_bf16_f32 v56, v60, v56
	v_cvt_pk_bf16_f32 v57, v61, v57
	v_lshl_add_u64 v[60:61], s[92:93], 0, v[76:77]
	v_pk_mul_f32 v[52:53], v[64:65], v[52:53]
	v_cvt_pk_bf16_f32 v58, v62, v58
	v_cvt_pk_bf16_f32 v59, v63, v59
	v_lshl_add_u64 v[60:61], v[60:61], 0, v[196:197]
	v_pk_add_f32 v[48:49], v[48:49], v[72:73]
	v_pk_mul_f32 v[54:55], v[66:67], v[54:55]
	v_pk_mul_f32 v[52:53], v[52:53], s[62:63] op_sel_hi:[1,0]
	v_pk_add_f32 v[44:45], v[44:45], v[100:101]
	global_store_dwordx4 v[60:61], v[56:59], off
	v_lshlrev_b32_e32 v221, 16, v56
	v_lshlrev_b32_e32 v222, 16, v57
	v_lshlrev_b32_e32 v223, 16, v58
	v_lshlrev_b32_e32 v224, 16, v59
	v_and_b32_e32 v225, 0xffff0000, v56
	v_and_b32_e32 v226, 0xffff0000, v57
	v_and_b32_e32 v227, 0xffff0000, v58
	v_and_b32_e32 v228, 0xffff0000, v59
	v_exp_f32_e32 v221, v221
	v_exp_f32_e32 v222, v222
	v_exp_f32_e32 v223, v223
	v_exp_f32_e32 v224, v224
	v_fmac_f32_dpp v225, v225, v221 row_shr:1 row_mask:0xf bank_mask:0xf
	v_fmac_f32_dpp v226, v226, v222 row_shr:1 row_mask:0xf bank_mask:0xf
	v_fmac_f32_dpp v227, v227, v223 row_shr:1 row_mask:0xf bank_mask:0xf
	v_fmac_f32_dpp v228, v228, v224 row_shr:1 row_mask:0xf bank_mask:0xf
	v_mul_f32_dpp v221, v221, v221 row_shr:1 row_mask:0xf bank_mask:0xf
	v_mul_f32_dpp v222, v222, v222 row_shr:1 row_mask:0xf bank_mask:0xf
	v_mul_f32_dpp v223, v223, v223 row_shr:1 row_mask:0xf bank_mask:0xf
	v_mul_f32_dpp v224, v224, v224 row_shr:1 row_mask:0xf bank_mask:0xf
	v_fmac_f32_dpp v225, v225, v221 row_shr:2 row_mask:0xf bank_mask:0xf
	v_fmac_f32_dpp v226, v226, v222 row_shr:2 row_mask:0xf bank_mask:0xf
	v_fmac_f32_dpp v227, v227, v223 row_shr:2 row_mask:0xf bank_mask:0xf
	v_fmac_f32_dpp v228, v228, v224 row_shr:2 row_mask:0xf bank_mask:0xf
	v_mul_f32_dpp v221, v221, v221 row_shr:2 row_mask:0xf bank_mask:0xf
	v_mul_f32_dpp v222, v222, v222 row_shr:2 row_mask:0xf bank_mask:0xf
	v_mul_f32_dpp v223, v223, v223 row_shr:2 row_mask:0xf bank_mask:0xf
	v_mul_f32_dpp v224, v224, v224 row_shr:2 row_mask:0xf bank_mask:0xf
	v_fmac_f32_dpp v225, v225, v221 row_shr:4 row_mask:0xf bank_mask:0xf
	v_fmac_f32_dpp v226, v226, v222 row_shr:4 row_mask:0xf bank_mask:0xf
	v_fmac_f32_dpp v227, v227, v223 row_shr:4 row_mask:0xf bank_mask:0xf
	v_fmac_f32_dpp v228, v228, v224 row_shr:4 row_mask:0xf bank_mask:0xf
	v_mul_f32_dpp v221, v221, v221 row_shr:4 row_mask:0xf bank_mask:0xf
	v_mul_f32_dpp v222, v222, v222 row_shr:4 row_mask:0xf bank_mask:0xf
	v_mul_f32_dpp v223, v223, v223 row_shr:4 row_mask:0xf bank_mask:0xf
	v_mul_f32_dpp v224, v224, v224 row_shr:4 row_mask:0xf bank_mask:0xf
	v_fmac_f32_dpp v225, v225, v221 row_shr:8 row_mask:0xf bank_mask:0xf
; __device__ __forceinline__ unsigned cvt_pk_bf16(float lo, float hi) { unsigned r; asm volatile("v_cvt_pk_bf16_f32 %0, %1, %2" : "=v"(r) : "v"(lo), "v"(hi)); return r; }
; __device__ __forceinline__ float bf_lo(unsigned w) { return __uint_as_float(w << 16); }
; __device__ __forceinline__ float bf_hi(unsigned w) { return __uint_as_float(w & 0xffff0000u); }
;     __device__ __forceinline__ void operator()(EPI_ARGS) const {
;     ...
;                     const unsigned w0 = n ? vv[ai][m].z : vv[ai][m].x, w1 = n ? vv[ai][m].w : vv[ai][m].y;
;                     const f32x4 vx = (f32x4){bf_lo(w0), bf_hi(w0), bf_lo(w1), bf_hi(w1)};
;                     const f32x4 r = sigmoid4(acc[ai][0][m][n] + ba[n]), ig = sigmoid4(acc[ai][1][m][n] + bi[n]);
;                     const f32x4 la = sp[n] * r * (-1.4426950409f);
;                     f32x4 av;
; #pragma unroll
;                     for (int j = 0; j < 4; ++j) av[j] = __builtin_amdgcn_exp2f(la[j]);
;                     const f32x4 om = 1.0f - av * av; f32x4 sq;
; #pragma unroll
;                     for (int j = 0; j < 4; ++j) sq[j] = __builtin_amdgcn_sqrtf(om[j]);
;                     const f32x4 bx = sq * ig * vx;
;                     u32x4 w; w.x = cvt_pk_bf16(la[0], bx[0]); w.y = cvt_pk_bf16(la[1], bx[1]); w.z = cvt_pk_bf16(la[2], bx[2]); w.w = cvt_pk_bf16(la[3], bx[3]);
;                     *(u32x4*)(AB + (size_t)row * LW + c0 + 4 * n) = w;
; __global__ void __launch_bounds__(NTHR, 2) hybrid_block_fwd(Args a) {
;     ...
;         for (int i = 0; i < CH_L; ++i) { const u32x2 q = pab[(size_t)i * (LW / 2)];
;             const f32x2 av = (f32x2){__builtin_amdgcn_exp2f(bf_lo(q.x)), __builtin_amdgcn_exp2f(bf_lo(q.y))}, bv = (f32x2){bf_hi(q.x), bf_hi(q.y)}; P = P * av; H = av * H + bv; }
	v_fmac_f32_dpp v226, v226, v222 row_shr:8 row_mask:0xf bank_mask:0xf
	v_fmac_f32_dpp v227, v227, v223 row_shr:8 row_mask:0xf bank_mask:0xf
	v_fmac_f32_dpp v228, v228, v224 row_shr:8 row_mask:0xf bank_mask:0xf
	v_mul_f32_dpp v221, v221, v221 row_shr:8 row_mask:0xf bank_mask:0xf
	v_mul_f32_dpp v222, v222, v222 row_shr:8 row_mask:0xf bank_mask:0xf
	v_mul_f32_dpp v223, v223, v223 row_shr:8 row_mask:0xf bank_mask:0xf
	v_mul_f32_dpp v224, v224, v224 row_shr:8 row_mask:0xf bank_mask:0xf
	v_mov_b32_e32 v230, v221
	v_mov_b32_e32 v231, v222
	v_mov_b32_e32 v232, v223
	v_mov_b32_e32 v233, v224
	v_mov_b32_e32 v234, v225
	v_mov_b32_e32 v235, v226
	v_mov_b32_e32 v236, v227
	v_mov_b32_e32 v237, v228
	v_pk_add_f32 v[50:51], v[50:51], v[74:75]
	v_mul_f32_e32 v48, 0xbfb8aa3b, v48
	v_mul_f32_e32 v49, 0xbfb8aa3b, v49
	v_pk_mul_f32 v[54:55], v[54:55], s[62:63] op_sel_hi:[1,0]
	v_exp_f32_e32 v58, v52
	v_exp_f32_e32 v59, v53
	v_pk_add_f32 v[46:47], v[46:47], v[102:103]
	v_mul_f32_e32 v44, 0xbfb8aa3b, v44
	v_mul_f32_e32 v45, 0xbfb8aa3b, v45
	v_exp_f32_e32 v48, v48
	v_exp_f32_e32 v49, v49
	v_mul_f32_e32 v50, 0xbfb8aa3b, v50
	v_mul_f32_e32 v51, 0xbfb8aa3b, v51
	v_exp_f32_e32 v62, v54
	v_exp_f32_e32 v63, v55
	v_exp_f32_e32 v44, v44
	v_exp_f32_e32 v45, v45
	v_mul_f32_e32 v46, 0xbfb8aa3b, v46
	v_mul_f32_e32 v47, 0xbfb8aa3b, v47
	v_exp_f32_e32 v50, v50
	v_exp_f32_e32 v51, v51
	v_exp_f32_e32 v46, v46
	v_exp_f32_e32 v47, v47
	v_pk_mul_f32 v[58:59], v[58:59], v[58:59]
	v_add_f32_e32 v48, 1.0, v48
	v_add_f32_e32 v49, 1.0, v49
	v_pk_mul_f32 v[62:63], v[62:63], v[62:63]
	v_sub_f32_e32 v58, 1.0, v58
	v_sub_f32_e32 v59, 1.0, v59
	v_add_f32_e32 v44, 1.0, v44
	v_add_f32_e32 v45, 1.0, v45
	v_rcp_f32_e32 v48, v48
	v_rcp_f32_e32 v49, v49
	v_add_f32_e32 v50, 1.0, v50
	v_add_f32_e32 v51, 1.0, v51
	v_sqrt_f32_e32 v58, v58
	v_sub_f32_e32 v62, 1.0, v62
	v_sub_f32_e32 v63, 1.0, v63
	v_sqrt_f32_e32 v59, v59
	v_rcp_f32_e32 v44, v44
	v_rcp_f32_e32 v45, v45
	v_add_f32_e32 v46, 1.0, v46
	v_add_f32_e32 v47, 1.0, v47
	v_rcp_f32_e32 v50, v50
	v_rcp_f32_e32 v51, v51
	v_sqrt_f32_e32 v62, v62
	v_sqrt_f32_e32 v63, v63
	v_rcp_f32_e32 v46, v46
	v_rcp_f32_e32 v47, v47
	v_lshlrev_b32_e32 v56, 16, v150
	v_and_b32_e32 v57, 0xffff0000, v150
	v_pk_mul_f32 v[48:49], v[48:49], v[58:59]
	v_pk_mul_f32 v[44:45], v[88:89], v[44:45]
	v_lshlrev_b32_e32 v76, 16, v151
	v_and_b32_e32 v77, 0xffff0000, v151
	v_pk_mul_f32 v[50:51], v[50:51], v[62:63]
	v_pk_mul_f32 v[48:49], v[48:49], v[56:57]
	v_pk_add_f32 v[40:41], v[40:41], v[92:93]
	v_pk_mul_f32 v[46:47], v[90:91], v[46:47]
	v_pk_mul_f32 v[44:45], v[44:45], s[62:63] op_sel_hi:[1,0]
	v_pk_mul_f32 v[50:51], v[50:51], v[76:77]
	v_cvt_pk_bf16_f32 v48, v52, v48
	v_cvt_pk_bf16_f32 v49, v53, v49
	v_pk_add_f32 v[42:43], v[42:43], v[94:95]
	v_mul_f32_e32 v40, 0xbfb8aa3b, v40
	v_mul_f32_e32 v41, 0xbfb8aa3b, v41
	v_pk_mul_f32 v[46:47], v[46:47], s[62:63] op_sel_hi:[1,0]
	v_exp_f32_e32 v52, v44
	v_exp_f32_e32 v53, v45
	v_cvt_pk_bf16_f32 v50, v54, v50
	v_cvt_pk_bf16_f32 v51, v55, v51
	v_exp_f32_e32 v40, v40
	v_exp_f32_e32 v41, v41
	v_mul_f32_e32 v42, 0xbfb8aa3b, v42
	v_mul_f32_e32 v43, 0xbfb8aa3b, v43
	v_exp_f32_e32 v54, v46
	v_exp_f32_e32 v55, v47
	v_pk_add_f32 v[36:37], v[36:37], v[80:81]
	v_exp_f32_e32 v42, v42
	v_exp_f32_e32 v43, v43
	v_pk_add_f32 v[38:39], v[38:39], v[82:83]
	v_mul_f32_e32 v36, 0xbfb8aa3b, v36
	v_mul_f32_e32 v37, 0xbfb8aa3b, v37
	v_exp_f32_e32 v36, v36
	v_exp_f32_e32 v37, v37
	v_mul_f32_e32 v38, 0xbfb8aa3b, v38
	v_mul_f32_e32 v39, 0xbfb8aa3b, v39
	v_pk_mul_f32 v[52:53], v[52:53], v[52:53]
	v_exp_f32_e32 v38, v38
	v_exp_f32_e32 v39, v39
	v_add_f32_e32 v40, 1.0, v40
	v_add_f32_e32 v41, 1.0, v41
	v_pk_mul_f32 v[54:55], v[54:55], v[54:55]
	v_sub_f32_e32 v52, 1.0, v52
	v_sub_f32_e32 v53, 1.0, v53
	v_rcp_f32_e32 v40, v40
	v_rcp_f32_e32 v41, v41
	v_add_f32_e32 v42, 1.0, v42
	v_add_f32_e32 v43, 1.0, v43
	v_sqrt_f32_e32 v52, v52
	v_sub_f32_e32 v54, 1.0, v54
	v_sub_f32_e32 v55, 1.0, v55
	v_sqrt_f32_e32 v53, v53
	v_rcp_f32_e32 v42, v42
	v_rcp_f32_e32 v43, v43
	v_sqrt_f32_e32 v54, v54
	v_sqrt_f32_e32 v55, v55
	v_add_f32_e32 v36, 1.0, v36
	v_add_f32_e32 v37, 1.0, v37
	v_rcp_f32_e32 v36, v36
	v_rcp_f32_e32 v37, v37
	v_add_f32_e32 v38, 1.0, v38
	v_add_f32_e32 v39, 1.0, v39
	v_rcp_f32_e32 v38, v38
	v_rcp_f32_e32 v39, v39
	global_store_dwordx4 v[60:61], v[48:51], off offset:16
	v_lshlrev_b32_e32 v221, 16, v48
	v_lshlrev_b32_e32 v222, 16, v49
	v_lshlrev_b32_e32 v223, 16, v50
	v_lshlrev_b32_e32 v224, 16, v51
	v_and_b32_e32 v225, 0xffff0000, v48
	v_and_b32_e32 v226, 0xffff0000, v49
	v_and_b32_e32 v227, 0xffff0000, v50
	v_and_b32_e32 v228, 0xffff0000, v51
	v_exp_f32_e32 v221, v221
	v_exp_f32_e32 v222, v222
	v_exp_f32_e32 v223, v223
	v_exp_f32_e32 v224, v224
	v_fmac_f32_dpp v225, v225, v221 row_shr:1 row_mask:0xf bank_mask:0xf
	v_fmac_f32_dpp v226, v226, v222 row_shr:1 row_mask:0xf bank_mask:0xf
	v_fmac_f32_dpp v227, v227, v223 row_shr:1 row_mask:0xf bank_mask:0xf
	v_fmac_f32_dpp v228, v228, v224 row_shr:1 row_mask:0xf bank_mask:0xf
	v_mul_f32_dpp v221, v221, v221 row_shr:1 row_mask:0xf bank_mask:0xf
	v_mul_f32_dpp v222, v222, v222 row_shr:1 row_mask:0xf bank_mask:0xf
	v_mul_f32_dpp v223, v223, v223 row_shr:1 row_mask:0xf bank_mask:0xf
	v_mul_f32_dpp v224, v224, v224 row_shr:1 row_mask:0xf bank_mask:0xf
	v_fmac_f32_dpp v225, v225, v221 row_shr:2 row_mask:0xf bank_mask:0xf
	v_fmac_f32_dpp v226, v226, v222 row_shr:2 row_mask:0xf bank_mask:0xf
	v_fmac_f32_dpp v227, v227, v223 row_shr:2 row_mask:0xf bank_mask:0xf
	v_fmac_f32_dpp v228, v228, v224 row_shr:2 row_mask:0xf bank_mask:0xf
	v_mul_f32_dpp v221, v221, v221 row_shr:2 row_mask:0xf bank_mask:0xf
; __device__ __forceinline__ unsigned cvt_pk_bf16(float lo, float hi) { unsigned r; asm volatile("v_cvt_pk_bf16_f32 %0, %1, %2" : "=v"(r) : "v"(lo), "v"(hi)); return r; }
; __device__ __forceinline__ float bf_lo(unsigned w) { return __uint_as_float(w << 16); }
; __device__ __forceinline__ float bf_hi(unsigned w) { return __uint_as_float(w & 0xffff0000u); }
;     __device__ __forceinline__ void operator()(EPI_ARGS) const {
;     ...
;                     const unsigned w0 = n ? vv[ai][m].z : vv[ai][m].x, w1 = n ? vv[ai][m].w : vv[ai][m].y;
;                     const f32x4 vx = (f32x4){bf_lo(w0), bf_hi(w0), bf_lo(w1), bf_hi(w1)};
;                     const f32x4 r = sigmoid4(acc[ai][0][m][n] + ba[n]), ig = sigmoid4(acc[ai][1][m][n] + bi[n]);
;                     const f32x4 la = sp[n] * r * (-1.4426950409f);
;                     f32x4 av;
; #pragma unroll
;                     for (int j = 0; j < 4; ++j) av[j] = __builtin_amdgcn_exp2f(la[j]);
;                     const f32x4 om = 1.0f - av * av; f32x4 sq;
; #pragma unroll
;                     for (int j = 0; j < 4; ++j) sq[j] = __builtin_amdgcn_sqrtf(om[j]);
;                     const f32x4 bx = sq * ig * vx;
;                     u32x4 w; w.x = cvt_pk_bf16(la[0], bx[0]); w.y = cvt_pk_bf16(la[1], bx[1]); w.z = cvt_pk_bf16(la[2], bx[2]); w.w = cvt_pk_bf16(la[3], bx[3]);
;                     *(u32x4*)(AB + (size_t)row * LW + c0 + 4 * n) = w;
; __global__ void __launch_bounds__(NTHR, 2) hybrid_block_fwd(Args a) {
;     ...
;         for (int i = 0; i < CH_L; ++i) { const u32x2 q = pab[(size_t)i * (LW / 2)];
;             const f32x2 av = (f32x2){__builtin_amdgcn_exp2f(bf_lo(q.x)), __builtin_amdgcn_exp2f(bf_lo(q.y))}, bv = (f32x2){bf_hi(q.x), bf_hi(q.y)}; P = P * av; H = av * H + bv; }
	v_mul_f32_dpp v222, v222, v222 row_shr:2 row_mask:0xf bank_mask:0xf
	v_mul_f32_dpp v223, v223, v223 row_shr:2 row_mask:0xf bank_mask:0xf
	v_mul_f32_dpp v224, v224, v224 row_shr:2 row_mask:0xf bank_mask:0xf
	v_fmac_f32_dpp v225, v225, v221 row_shr:4 row_mask:0xf bank_mask:0xf
	v_fmac_f32_dpp v226, v226, v222 row_shr:4 row_mask:0xf bank_mask:0xf
	v_fmac_f32_dpp v227, v227, v223 row_shr:4 row_mask:0xf bank_mask:0xf
	v_fmac_f32_dpp v228, v228, v224 row_shr:4 row_mask:0xf bank_mask:0xf
	v_mul_f32_dpp v221, v221, v221 row_shr:4 row_mask:0xf bank_mask:0xf
	v_mul_f32_dpp v222, v222, v222 row_shr:4 row_mask:0xf bank_mask:0xf
	v_mul_f32_dpp v223, v223, v223 row_shr:4 row_mask:0xf bank_mask:0xf
	v_mul_f32_dpp v224, v224, v224 row_shr:4 row_mask:0xf bank_mask:0xf
	v_fmac_f32_dpp v225, v225, v221 row_shr:8 row_mask:0xf bank_mask:0xf
	v_fmac_f32_dpp v226, v226, v222 row_shr:8 row_mask:0xf bank_mask:0xf
	v_fmac_f32_dpp v227, v227, v223 row_shr:8 row_mask:0xf bank_mask:0xf
	v_fmac_f32_dpp v228, v228, v224 row_shr:8 row_mask:0xf bank_mask:0xf
	v_mul_f32_dpp v221, v221, v221 row_shr:8 row_mask:0xf bank_mask:0xf
	v_mul_f32_dpp v222, v222, v222 row_shr:8 row_mask:0xf bank_mask:0xf
	v_mul_f32_dpp v223, v223, v223 row_shr:8 row_mask:0xf bank_mask:0xf
	v_mul_f32_dpp v224, v224, v224 row_shr:8 row_mask:0xf bank_mask:0xf
	v_mov_b32_e32 v238, v221
	v_mov_b32_e32 v239, v222
	v_mov_b32_e32 v240, v223
	v_mov_b32_e32 v241, v224
	v_mov_b32_e32 v242, v225
	v_mov_b32_e32 v243, v226
	v_mov_b32_e32 v244, v227
	v_mov_b32_e32 v245, v228
	v_pk_mul_f32 v[40:41], v[40:41], v[52:53]
	v_lshlrev_b32_e32 v56, 16, v129
	v_lshlrev_b32_e32 v50, 16, v128
	v_and_b32_e32 v51, 0xffff0000, v128
	v_lshlrev_b64 v[48:49], 13, v[202:203]
	v_and_b32_e32 v57, 0xffff0000, v129
	v_pk_mul_f32 v[42:43], v[42:43], v[54:55]
	v_pk_mul_f32 v[40:41], v[40:41], v[50:51]
	v_pk_mul_f32 v[42:43], v[42:43], v[56:57]
	v_cvt_pk_bf16_f32 v40, v44, v40
	v_cvt_pk_bf16_f32 v41, v45, v41
	v_lshl_add_u64 v[44:45], s[92:93], 0, v[48:49]
	v_pk_mul_f32 v[36:37], v[64:65], v[36:37]
	v_cvt_pk_bf16_f32 v42, v46, v42
	v_cvt_pk_bf16_f32 v43, v47, v43
	v_lshl_add_u64 v[44:45], v[44:45], 0, v[196:197]
	v_pk_add_f32 v[32:33], v[32:33], v[72:73]
	v_pk_mul_f32 v[38:39], v[66:67], v[38:39]
	v_pk_mul_f32 v[36:37], v[36:37], s[62:63] op_sel_hi:[1,0]
	v_pk_add_f32 v[28:29], v[28:29], v[100:101]
	global_store_dwordx4 v[44:45], v[40:43], off
	v_lshlrev_b32_e32 v221, 16, v40
	v_lshlrev_b32_e32 v222, 16, v41
	v_lshlrev_b32_e32 v223, 16, v42
	v_lshlrev_b32_e32 v224, 16, v43
	v_and_b32_e32 v225, 0xffff0000, v40
	v_and_b32_e32 v226, 0xffff0000, v41
	v_and_b32_e32 v227, 0xffff0000, v42
	v_and_b32_e32 v228, 0xffff0000, v43
	v_exp_f32_e32 v221, v221
	v_exp_f32_e32 v222, v222
	v_exp_f32_e32 v223, v223
	v_exp_f32_e32 v224, v224
	v_fmac_f32_dpp v225, v225, v221 row_shr:1 row_mask:0xf bank_mask:0xf
	v_fmac_f32_dpp v226, v226, v222 row_shr:1 row_mask:0xf bank_mask:0xf
	v_fmac_f32_dpp v227, v227, v223 row_shr:1 row_mask:0xf bank_mask:0xf
	v_fmac_f32_dpp v228, v228, v224 row_shr:1 row_mask:0xf bank_mask:0xf
	v_mul_f32_dpp v221, v221, v221 row_shr:1 row_mask:0xf bank_mask:0xf
	v_mul_f32_dpp v222, v222, v222 row_shr:1 row_mask:0xf bank_mask:0xf
	v_mul_f32_dpp v223, v223, v223 row_shr:1 row_mask:0xf bank_mask:0xf
	v_mul_f32_dpp v224, v224, v224 row_shr:1 row_mask:0xf bank_mask:0xf
	v_fmac_f32_dpp v225, v225, v221 row_shr:2 row_mask:0xf bank_mask:0xf
	v_fmac_f32_dpp v226, v226, v222 row_shr:2 row_mask:0xf bank_mask:0xf
	v_fmac_f32_dpp v227, v227, v223 row_shr:2 row_mask:0xf bank_mask:0xf
	v_fmac_f32_dpp v228, v228, v224 row_shr:2 row_mask:0xf bank_mask:0xf
	v_mul_f32_dpp v221, v221, v221 row_shr:2 row_mask:0xf bank_mask:0xf
	v_mul_f32_dpp v222, v222, v222 row_shr:2 row_mask:0xf bank_mask:0xf
	v_mul_f32_dpp v223, v223, v223 row_shr:2 row_mask:0xf bank_mask:0xf
	v_mul_f32_dpp v224, v224, v224 row_shr:2 row_mask:0xf bank_mask:0xf
	v_fmac_f32_dpp v225, v225, v221 row_shr:4 row_mask:0xf bank_mask:0xf
	v_fmac_f32_dpp v226, v226, v222 row_shr:4 row_mask:0xf bank_mask:0xf
	v_fmac_f32_dpp v227, v227, v223 row_shr:4 row_mask:0xf bank_mask:0xf
	v_fmac_f32_dpp v228, v228, v224 row_shr:4 row_mask:0xf bank_mask:0xf
	v_mul_f32_dpp v221, v221, v221 row_shr:4 row_mask:0xf bank_mask:0xf
	v_mul_f32_dpp v222, v222, v222 row_shr:4 row_mask:0xf bank_mask:0xf
	v_mul_f32_dpp v223, v223, v223 row_shr:4 row_mask:0xf bank_mask:0xf
	v_mul_f32_dpp v224, v224, v224 row_shr:4 row_mask:0xf bank_mask:0xf
	v_fmac_f32_dpp v225, v225, v221 row_shr:8 row_mask:0xf bank_mask:0xf
	v_fmac_f32_dpp v226, v226, v222 row_shr:8 row_mask:0xf bank_mask:0xf
	v_fmac_f32_dpp v227, v227, v223 row_shr:8 row_mask:0xf bank_mask:0xf
	v_fmac_f32_dpp v228, v228, v224 row_shr:8 row_mask:0xf bank_mask:0xf
	v_mul_f32_dpp v221, v221, v221 row_shr:8 row_mask:0xf bank_mask:0xf
	v_mul_f32_dpp v222, v222, v222 row_shr:8 row_mask:0xf bank_mask:0xf
	v_mul_f32_dpp v223, v223, v223 row_shr:8 row_mask:0xf bank_mask:0xf
	v_mul_f32_dpp v224, v224, v224 row_shr:8 row_mask:0xf bank_mask:0xf
	v_fma_f32 v234, v234, v221, v225
	v_fma_f32 v235, v235, v222, v226
	v_fma_f32 v236, v236, v223, v227
	v_fma_f32 v237, v237, v224, v228
	v_mul_f32_e32 v230, v230, v221
	v_mul_f32_e32 v231, v231, v222
	v_mul_f32_e32 v232, v232, v223
	v_mul_f32_e32 v233, v233, v224
	v_pk_add_f32 v[34:35], v[34:35], v[74:75]
	v_mul_f32_e32 v32, 0xbfb8aa3b, v32
	v_mul_f32_e32 v33, 0xbfb8aa3b, v33
	v_pk_mul_f32 v[38:39], v[38:39], s[62:63] op_sel_hi:[1,0]
	v_exp_f32_e32 v42, v36
	v_exp_f32_e32 v43, v37
	v_pk_add_f32 v[30:31], v[30:31], v[102:103]
	v_mul_f32_e32 v28, 0xbfb8aa3b, v28
	v_mul_f32_e32 v29, 0xbfb8aa3b, v29
	v_exp_f32_e32 v32, v32
	v_exp_f32_e32 v33, v33
; __device__ __forceinline__ unsigned cvt_pk_bf16(float lo, float hi) { unsigned r; asm volatile("v_cvt_pk_bf16_f32 %0, %1, %2" : "=v"(r) : "v"(lo), "v"(hi)); return r; }
; __device__ __forceinline__ float bf_lo(unsigned w) { return __uint_as_float(w << 16); }
; __device__ __forceinline__ float bf_hi(unsigned w) { return __uint_as_float(w & 0xffff0000u); }
;     __device__ __forceinline__ void operator()(EPI_ARGS) const {
;     ...
;                     const unsigned w0 = n ? vv[ai][m].z : vv[ai][m].x, w1 = n ? vv[ai][m].w : vv[ai][m].y;
;                     const f32x4 vx = (f32x4){bf_lo(w0), bf_hi(w0), bf_lo(w1), bf_hi(w1)};
;                     const f32x4 r = sigmoid4(acc[ai][0][m][n] + ba[n]), ig = sigmoid4(acc[ai][1][m][n] + bi[n]);
;                     const f32x4 la = sp[n] * r * (-1.4426950409f);
;                     f32x4 av;
; #pragma unroll
;                     for (int j = 0; j < 4; ++j) av[j] = __builtin_amdgcn_exp2f(la[j]);
;                     const f32x4 om = 1.0f - av * av; f32x4 sq;
; #pragma unroll
;                     for (int j = 0; j < 4; ++j) sq[j] = __builtin_amdgcn_sqrtf(om[j]);
;                     const f32x4 bx = sq * ig * vx;
;                     u32x4 w; w.x = cvt_pk_bf16(la[0], bx[0]); w.y = cvt_pk_bf16(la[1], bx[1]); w.z = cvt_pk_bf16(la[2], bx[2]); w.w = cvt_pk_bf16(la[3], bx[3]);
;                     *(u32x4*)(AB + (size_t)row * LW + c0 + 4 * n) = w;
; __global__ void __launch_bounds__(NTHR, 2) hybrid_block_fwd(Args a) {
;     ...
;         for (int i = 0; i < CH_L; ++i) { const u32x2 q = pab[(size_t)i * (LW / 2)];
;             const f32x2 av = (f32x2){__builtin_amdgcn_exp2f(bf_lo(q.x)), __builtin_amdgcn_exp2f(bf_lo(q.y))}, bv = (f32x2){bf_hi(q.x), bf_hi(q.y)}; P = P * av; H = av * H + bv; }
	v_mul_f32_e32 v34, 0xbfb8aa3b, v34
	v_mul_f32_e32 v35, 0xbfb8aa3b, v35
	v_exp_f32_e32 v46, v38
	v_exp_f32_e32 v47, v39
	v_exp_f32_e32 v28, v28
	v_exp_f32_e32 v29, v29
	v_mul_f32_e32 v30, 0xbfb8aa3b, v30
	v_mul_f32_e32 v31, 0xbfb8aa3b, v31
	v_exp_f32_e32 v34, v34
	v_exp_f32_e32 v35, v35
	v_exp_f32_e32 v30, v30
	v_exp_f32_e32 v31, v31
	v_pk_mul_f32 v[42:43], v[42:43], v[42:43]
	v_add_f32_e32 v32, 1.0, v32
	v_add_f32_e32 v33, 1.0, v33
	v_pk_mul_f32 v[46:47], v[46:47], v[46:47]
	v_sub_f32_e32 v42, 1.0, v42
	v_sub_f32_e32 v43, 1.0, v43
	v_add_f32_e32 v28, 1.0, v28
	v_add_f32_e32 v29, 1.0, v29
	v_rcp_f32_e32 v32, v32
	v_rcp_f32_e32 v33, v33
	v_add_f32_e32 v34, 1.0, v34
	v_add_f32_e32 v35, 1.0, v35
	v_sqrt_f32_e32 v42, v42
	v_sub_f32_e32 v46, 1.0, v46
	v_sub_f32_e32 v47, 1.0, v47
	v_sqrt_f32_e32 v43, v43
	v_rcp_f32_e32 v28, v28
	v_rcp_f32_e32 v29, v29
	v_add_f32_e32 v30, 1.0, v30
	v_add_f32_e32 v31, 1.0, v31
	v_rcp_f32_e32 v34, v34
	v_rcp_f32_e32 v35, v35
	v_sqrt_f32_e32 v46, v46
	v_sqrt_f32_e32 v47, v47
	v_rcp_f32_e32 v30, v30
	v_rcp_f32_e32 v31, v31
	v_lshlrev_b32_e32 v40, 16, v130
	v_and_b32_e32 v41, 0xffff0000, v130
	v_pk_mul_f32 v[32:33], v[32:33], v[42:43]
	v_pk_mul_f32 v[28:29], v[88:89], v[28:29]
	v_lshlrev_b32_e32 v48, 16, v131
	v_and_b32_e32 v49, 0xffff0000, v131
	v_pk_mul_f32 v[34:35], v[34:35], v[46:47]
	v_pk_mul_f32 v[32:33], v[32:33], v[40:41]
	v_pk_add_f32 v[24:25], v[24:25], v[92:93]
	v_pk_mul_f32 v[30:31], v[90:91], v[30:31]
	v_pk_mul_f32 v[28:29], v[28:29], s[62:63] op_sel_hi:[1,0]
	v_pk_mul_f32 v[34:35], v[34:35], v[48:49]
	v_cvt_pk_bf16_f32 v32, v36, v32
	v_cvt_pk_bf16_f32 v33, v37, v33
	v_pk_add_f32 v[26:27], v[26:27], v[94:95]
	v_mul_f32_e32 v24, 0xbfb8aa3b, v24
	v_mul_f32_e32 v25, 0xbfb8aa3b, v25
	v_pk_mul_f32 v[30:31], v[30:31], s[62:63] op_sel_hi:[1,0]
	v_exp_f32_e32 v36, v28
	v_exp_f32_e32 v37, v29
	v_cvt_pk_bf16_f32 v34, v38, v34
	v_cvt_pk_bf16_f32 v35, v39, v35
	v_exp_f32_e32 v24, v24
	v_exp_f32_e32 v25, v25
	v_mul_f32_e32 v26, 0xbfb8aa3b, v26
	v_mul_f32_e32 v27, 0xbfb8aa3b, v27
	v_exp_f32_e32 v38, v30
	v_exp_f32_e32 v39, v31
	v_pk_add_f32 v[20:21], v[20:21], v[80:81]
	v_exp_f32_e32 v26, v26
	v_exp_f32_e32 v27, v27
	v_pk_add_f32 v[22:23], v[22:23], v[82:83]
	v_mul_f32_e32 v20, 0xbfb8aa3b, v20
	v_mul_f32_e32 v21, 0xbfb8aa3b, v21
	v_exp_f32_e32 v20, v20
	v_exp_f32_e32 v21, v21
	v_mul_f32_e32 v22, 0xbfb8aa3b, v22
	v_mul_f32_e32 v23, 0xbfb8aa3b, v23
	v_pk_mul_f32 v[36:37], v[36:37], v[36:37]
	v_exp_f32_e32 v22, v22
	v_exp_f32_e32 v23, v23
	v_add_f32_e32 v24, 1.0, v24
	v_add_f32_e32 v25, 1.0, v25
	v_pk_mul_f32 v[38:39], v[38:39], v[38:39]
	v_sub_f32_e32 v36, 1.0, v36
	v_sub_f32_e32 v37, 1.0, v37
	v_rcp_f32_e32 v24, v24
	v_rcp_f32_e32 v25, v25
	v_add_f32_e32 v26, 1.0, v26
	v_add_f32_e32 v27, 1.0, v27
	v_sqrt_f32_e32 v36, v36
	v_sub_f32_e32 v38, 1.0, v38
	v_sub_f32_e32 v39, 1.0, v39
	v_sqrt_f32_e32 v37, v37
	v_rcp_f32_e32 v26, v26
	v_rcp_f32_e32 v27, v27
	v_sqrt_f32_e32 v38, v38
	v_sqrt_f32_e32 v39, v39
	v_add_f32_e32 v20, 1.0, v20
	v_add_f32_e32 v21, 1.0, v21
	v_rcp_f32_e32 v20, v20
	v_rcp_f32_e32 v21, v21
	v_add_f32_e32 v22, 1.0, v22
	v_add_f32_e32 v23, 1.0, v23
	v_rcp_f32_e32 v22, v22
	v_rcp_f32_e32 v23, v23
	global_store_dwordx4 v[44:45], v[32:35], off offset:16
	v_lshlrev_b32_e32 v221, 16, v32
	v_lshlrev_b32_e32 v222, 16, v33
	v_lshlrev_b32_e32 v223, 16, v34
	v_lshlrev_b32_e32 v224, 16, v35
	v_and_b32_e32 v225, 0xffff0000, v32
	v_and_b32_e32 v226, 0xffff0000, v33
	v_and_b32_e32 v227, 0xffff0000, v34
	v_and_b32_e32 v228, 0xffff0000, v35
	v_exp_f32_e32 v221, v221
	v_exp_f32_e32 v222, v222
	v_exp_f32_e32 v223, v223
	v_exp_f32_e32 v224, v224
	v_fmac_f32_dpp v225, v225, v221 row_shr:1 row_mask:0xf bank_mask:0xf
	v_fmac_f32_dpp v226, v226, v222 row_shr:1 row_mask:0xf bank_mask:0xf
	v_fmac_f32_dpp v227, v227, v223 row_shr:1 row_mask:0xf bank_mask:0xf
	v_fmac_f32_dpp v228, v228, v224 row_shr:1 row_mask:0xf bank_mask:0xf
	v_mul_f32_dpp v221, v221, v221 row_shr:1 row_mask:0xf bank_mask:0xf
	v_mul_f32_dpp v222, v222, v222 row_shr:1 row_mask:0xf bank_mask:0xf
	v_mul_f32_dpp v223, v223, v223 row_shr:1 row_mask:0xf bank_mask:0xf
	v_mul_f32_dpp v224, v224, v224 row_shr:1 row_mask:0xf bank_mask:0xf
	v_fmac_f32_dpp v225, v225, v221 row_shr:2 row_mask:0xf bank_mask:0xf
	v_fmac_f32_dpp v226, v226, v222 row_shr:2 row_mask:0xf bank_mask:0xf
	v_fmac_f32_dpp v227, v227, v223 row_shr:2 row_mask:0xf bank_mask:0xf
	v_fmac_f32_dpp v228, v228, v224 row_shr:2 row_mask:0xf bank_mask:0xf
	v_mul_f32_dpp v221, v221, v221 row_shr:2 row_mask:0xf bank_mask:0xf
	v_mul_f32_dpp v222, v222, v222 row_shr:2 row_mask:0xf bank_mask:0xf
	v_mul_f32_dpp v223, v223, v223 row_shr:2 row_mask:0xf bank_mask:0xf
	v_mul_f32_dpp v224, v224, v224 row_shr:2 row_mask:0xf bank_mask:0xf
	v_fmac_f32_dpp v225, v225, v221 row_shr:4 row_mask:0xf bank_mask:0xf
	v_fmac_f32_dpp v226, v226, v222 row_shr:4 row_mask:0xf bank_mask:0xf
	v_fmac_f32_dpp v227, v227, v223 row_shr:4 row_mask:0xf bank_mask:0xf
	v_fmac_f32_dpp v228, v228, v224 row_shr:4 row_mask:0xf bank_mask:0xf
	v_mul_f32_dpp v221, v221, v221 row_shr:4 row_mask:0xf bank_mask:0xf
	v_mul_f32_dpp v222, v222, v222 row_shr:4 row_mask:0xf bank_mask:0xf
	v_mul_f32_dpp v223, v223, v223 row_shr:4 row_mask:0xf bank_mask:0xf
	v_mul_f32_dpp v224, v224, v224 row_shr:4 row_mask:0xf bank_mask:0xf
	v_fmac_f32_dpp v225, v225, v221 row_shr:8 row_mask:0xf bank_mask:0xf
	v_fmac_f32_dpp v226, v226, v222 row_shr:8 row_mask:0xf bank_mask:0xf
	v_fmac_f32_dpp v227, v227, v223 row_shr:8 row_mask:0xf bank_mask:0xf
	v_fmac_f32_dpp v228, v228, v224 row_shr:8 row_mask:0xf bank_mask:0xf
	v_mul_f32_dpp v221, v221, v221 row_shr:8 row_mask:0xf bank_mask:0xf
; __device__ __forceinline__ unsigned cvt_pk_bf16(float lo, float hi) { unsigned r; asm volatile("v_cvt_pk_bf16_f32 %0, %1, %2" : "=v"(r) : "v"(lo), "v"(hi)); return r; }
; __device__ __forceinline__ float bf_lo(unsigned w) { return __uint_as_float(w << 16); }
; __device__ __forceinline__ float bf_hi(unsigned w) { return __uint_as_float(w & 0xffff0000u); }
;     __device__ __forceinline__ void operator()(EPI_ARGS) const {
;     ...
;                     const unsigned w0 = n ? vv[ai][m].z : vv[ai][m].x, w1 = n ? vv[ai][m].w : vv[ai][m].y;
;                     const f32x4 vx = (f32x4){bf_lo(w0), bf_hi(w0), bf_lo(w1), bf_hi(w1)};
;                     const f32x4 r = sigmoid4(acc[ai][0][m][n] + ba[n]), ig = sigmoid4(acc[ai][1][m][n] + bi[n]);
;                     const f32x4 la = sp[n] * r * (-1.4426950409f);
;                     f32x4 av;
; #pragma unroll
;                     for (int j = 0; j < 4; ++j) av[j] = __builtin_amdgcn_exp2f(la[j]);
;                     const f32x4 om = 1.0f - av * av; f32x4 sq;
; #pragma unroll
;                     for (int j = 0; j < 4; ++j) sq[j] = __builtin_amdgcn_sqrtf(om[j]);
;                     const f32x4 bx = sq * ig * vx;
;                     u32x4 w; w.x = cvt_pk_bf16(la[0], bx[0]); w.y = cvt_pk_bf16(la[1], bx[1]); w.z = cvt_pk_bf16(la[2], bx[2]); w.w = cvt_pk_bf16(la[3], bx[3]);
;                     *(u32x4*)(AB + (size_t)row * LW + c0 + 4 * n) = w;
; __global__ void __launch_bounds__(NTHR, 2) hybrid_block_fwd(Args a) {
;     ...
;         for (int i = 0; i < CH_L; ++i) { const u32x2 q = pab[(size_t)i * (LW / 2)];
;             const f32x2 av = (f32x2){__builtin_amdgcn_exp2f(bf_lo(q.x)), __builtin_amdgcn_exp2f(bf_lo(q.y))}, bv = (f32x2){bf_hi(q.x), bf_hi(q.y)}; P = P * av; H = av * H + bv; }
	v_mul_f32_dpp v222, v222, v222 row_shr:8 row_mask:0xf bank_mask:0xf
	v_mul_f32_dpp v223, v223, v223 row_shr:8 row_mask:0xf bank_mask:0xf
	v_mul_f32_dpp v224, v224, v224 row_shr:8 row_mask:0xf bank_mask:0xf
	v_fma_f32 v242, v242, v221, v225
	v_fma_f32 v243, v243, v222, v226
	v_fma_f32 v244, v244, v223, v227
	v_fma_f32 v245, v245, v224, v228
	v_mul_f32_e32 v238, v238, v221
	v_mul_f32_e32 v239, v239, v222
	v_mul_f32_e32 v240, v240, v223
	v_mul_f32_e32 v241, v241, v224
	v_pk_mul_f32 v[24:25], v[24:25], v[36:37]
	v_lshlrev_b32_e32 v40, 16, v109
	v_lshlrev_b32_e32 v34, 16, v108
	v_and_b32_e32 v35, 0xffff0000, v108
	v_lshlrev_b64 v[32:33], 13, v[200:201]
	v_and_b32_e32 v41, 0xffff0000, v109
	v_pk_mul_f32 v[26:27], v[26:27], v[38:39]
	v_pk_mul_f32 v[24:25], v[24:25], v[34:35]
	v_pk_mul_f32 v[26:27], v[26:27], v[40:41]
	v_cvt_pk_bf16_f32 v24, v28, v24
	v_cvt_pk_bf16_f32 v25, v29, v25
	v_lshl_add_u64 v[28:29], s[92:93], 0, v[32:33]
	v_pk_mul_f32 v[20:21], v[64:65], v[20:21]
	v_cvt_pk_bf16_f32 v26, v30, v26
	v_cvt_pk_bf16_f32 v27, v31, v27
	v_lshl_add_u64 v[28:29], v[28:29], 0, v[196:197]
	v_pk_add_f32 v[16:17], v[16:17], v[72:73]
	v_pk_mul_f32 v[22:23], v[66:67], v[22:23]
	v_pk_mul_f32 v[20:21], v[20:21], s[62:63] op_sel_hi:[1,0]
	v_pk_add_f32 v[12:13], v[12:13], v[100:101]
	global_store_dwordx4 v[28:29], v[24:27], off
	v_lshlrev_b32_e32 v221, 16, v24
	v_lshlrev_b32_e32 v222, 16, v25
	v_lshlrev_b32_e32 v223, 16, v26
	v_lshlrev_b32_e32 v224, 16, v27
	v_and_b32_e32 v225, 0xffff0000, v24
	v_and_b32_e32 v226, 0xffff0000, v25
	v_and_b32_e32 v227, 0xffff0000, v26
	v_and_b32_e32 v228, 0xffff0000, v27
	v_exp_f32_e32 v221, v221
	v_exp_f32_e32 v222, v222
	v_exp_f32_e32 v223, v223
	v_exp_f32_e32 v224, v224
	v_fmac_f32_dpp v225, v225, v221 row_shr:1 row_mask:0xf bank_mask:0xf
	v_fmac_f32_dpp v226, v226, v222 row_shr:1 row_mask:0xf bank_mask:0xf
	v_fmac_f32_dpp v227, v227, v223 row_shr:1 row_mask:0xf bank_mask:0xf
	v_fmac_f32_dpp v228, v228, v224 row_shr:1 row_mask:0xf bank_mask:0xf
	v_mul_f32_dpp v221, v221, v221 row_shr:1 row_mask:0xf bank_mask:0xf
	v_mul_f32_dpp v222, v222, v222 row_shr:1 row_mask:0xf bank_mask:0xf
	v_mul_f32_dpp v223, v223, v223 row_shr:1 row_mask:0xf bank_mask:0xf
	v_mul_f32_dpp v224, v224, v224 row_shr:1 row_mask:0xf bank_mask:0xf
	v_fmac_f32_dpp v225, v225, v221 row_shr:2 row_mask:0xf bank_mask:0xf
	v_fmac_f32_dpp v226, v226, v222 row_shr:2 row_mask:0xf bank_mask:0xf
	v_fmac_f32_dpp v227, v227, v223 row_shr:2 row_mask:0xf bank_mask:0xf
	v_fmac_f32_dpp v228, v228, v224 row_shr:2 row_mask:0xf bank_mask:0xf
	v_mul_f32_dpp v221, v221, v221 row_shr:2 row_mask:0xf bank_mask:0xf
	v_mul_f32_dpp v222, v222, v222 row_shr:2 row_mask:0xf bank_mask:0xf
	v_mul_f32_dpp v223, v223, v223 row_shr:2 row_mask:0xf bank_mask:0xf
	v_mul_f32_dpp v224, v224, v224 row_shr:2 row_mask:0xf bank_mask:0xf
	v_fmac_f32_dpp v225, v225, v221 row_shr:4 row_mask:0xf bank_mask:0xf
	v_fmac_f32_dpp v226, v226, v222 row_shr:4 row_mask:0xf bank_mask:0xf
	v_fmac_f32_dpp v227, v227, v223 row_shr:4 row_mask:0xf bank_mask:0xf
	v_fmac_f32_dpp v228, v228, v224 row_shr:4 row_mask:0xf bank_mask:0xf
	v_mul_f32_dpp v221, v221, v221 row_shr:4 row_mask:0xf bank_mask:0xf
	v_mul_f32_dpp v222, v222, v222 row_shr:4 row_mask:0xf bank_mask:0xf
	v_mul_f32_dpp v223, v223, v223 row_shr:4 row_mask:0xf bank_mask:0xf
	v_mul_f32_dpp v224, v224, v224 row_shr:4 row_mask:0xf bank_mask:0xf
	v_fmac_f32_dpp v225, v225, v221 row_shr:8 row_mask:0xf bank_mask:0xf
	v_fmac_f32_dpp v226, v226, v222 row_shr:8 row_mask:0xf bank_mask:0xf
	v_fmac_f32_dpp v227, v227, v223 row_shr:8 row_mask:0xf bank_mask:0xf
	v_fmac_f32_dpp v228, v228, v224 row_shr:8 row_mask:0xf bank_mask:0xf
	v_mul_f32_dpp v221, v221, v221 row_shr:8 row_mask:0xf bank_mask:0xf
	v_mul_f32_dpp v222, v222, v222 row_shr:8 row_mask:0xf bank_mask:0xf
	v_mul_f32_dpp v223, v223, v223 row_shr:8 row_mask:0xf bank_mask:0xf
	v_mul_f32_dpp v224, v224, v224 row_shr:8 row_mask:0xf bank_mask:0xf
	v_fma_f32 v234, v234, v221, v225
	v_fma_f32 v235, v235, v222, v226
	v_fma_f32 v236, v236, v223, v227
	v_fma_f32 v237, v237, v224, v228
	v_mul_f32_e32 v230, v230, v221
	v_mul_f32_e32 v231, v231, v222
	v_mul_f32_e32 v232, v232, v223
	v_mul_f32_e32 v233, v233, v224
	v_pk_add_f32 v[18:19], v[18:19], v[74:75]
	v_mul_f32_e32 v16, 0xbfb8aa3b, v16
	v_mul_f32_e32 v17, 0xbfb8aa3b, v17
	v_pk_mul_f32 v[22:23], v[22:23], s[62:63] op_sel_hi:[1,0]
	v_exp_f32_e32 v26, v20
	v_exp_f32_e32 v27, v21
	v_pk_add_f32 v[14:15], v[14:15], v[102:103]
	v_mul_f32_e32 v12, 0xbfb8aa3b, v12
	v_mul_f32_e32 v13, 0xbfb8aa3b, v13
	v_exp_f32_e32 v16, v16
	v_exp_f32_e32 v17, v17
	v_mul_f32_e32 v18, 0xbfb8aa3b, v18
	v_mul_f32_e32 v19, 0xbfb8aa3b, v19
	v_exp_f32_e32 v30, v22
	v_exp_f32_e32 v31, v23
	v_exp_f32_e32 v12, v12
	v_exp_f32_e32 v13, v13
	v_mul_f32_e32 v14, 0xbfb8aa3b, v14
	v_mul_f32_e32 v15, 0xbfb8aa3b, v15
	v_exp_f32_e32 v18, v18
	v_exp_f32_e32 v19, v19
	v_exp_f32_e32 v14, v14
	v_exp_f32_e32 v15, v15
	v_pk_mul_f32 v[26:27], v[26:27], v[26:27]
	v_add_f32_e32 v16, 1.0, v16
	v_add_f32_e32 v17, 1.0, v17
	v_pk_mul_f32 v[30:31], v[30:31], v[30:31]
	v_sub_f32_e32 v26, 1.0, v26
	v_sub_f32_e32 v27, 1.0, v27
	v_add_f32_e32 v12, 1.0, v12
	v_add_f32_e32 v13, 1.0, v13
	v_rcp_f32_e32 v16, v16
	v_rcp_f32_e32 v17, v17
	v_add_f32_e32 v18, 1.0, v18
	v_add_f32_e32 v19, 1.0, v19
	v_sqrt_f32_e32 v26, v26
	v_sub_f32_e32 v30, 1.0, v30
	v_sub_f32_e32 v31, 1.0, v31
	v_sqrt_f32_e32 v27, v27
	v_rcp_f32_e32 v12, v12
	v_rcp_f32_e32 v13, v13
	v_add_f32_e32 v14, 1.0, v14
	v_add_f32_e32 v15, 1.0, v15
	v_rcp_f32_e32 v18, v18
	v_rcp_f32_e32 v19, v19
	v_sqrt_f32_e32 v30, v30
	v_sqrt_f32_e32 v31, v31
	v_rcp_f32_e32 v14, v14
; __device__ __forceinline__ unsigned cvt_pk_bf16(float lo, float hi) { unsigned r; asm volatile("v_cvt_pk_bf16_f32 %0, %1, %2" : "=v"(r) : "v"(lo), "v"(hi)); return r; }
; __device__ __forceinline__ float bf_lo(unsigned w) { return __uint_as_float(w << 16); }
; __device__ __forceinline__ float bf_hi(unsigned w) { return __uint_as_float(w & 0xffff0000u); }
;     __device__ __forceinline__ void operator()(EPI_ARGS) const {
;     ...
;                     const f32x4 r = sigmoid4(acc[ai][0][m][n] + ba[n]), ig = sigmoid4(acc[ai][1][m][n] + bi[n]);
;                     const f32x4 la = sp[n] * r * (-1.4426950409f);
;                     f32x4 av;
; #pragma unroll
;                     for (int j = 0; j < 4; ++j) av[j] = __builtin_amdgcn_exp2f(la[j]);
;                     const f32x4 om = 1.0f - av * av; f32x4 sq;
; #pragma unroll
;                     for (int j = 0; j < 4; ++j) sq[j] = __builtin_amdgcn_sqrtf(om[j]);
;                     const f32x4 bx = sq * ig * vx;
;                     u32x4 w; w.x = cvt_pk_bf16(la[0], bx[0]); w.y = cvt_pk_bf16(la[1], bx[1]); w.z = cvt_pk_bf16(la[2], bx[2]); w.w = cvt_pk_bf16(la[3], bx[3]);
;                     *(u32x4*)(AB + (size_t)row * LW + c0 + 4 * n) = w;
; __global__ void __launch_bounds__(NTHR, 2) hybrid_block_fwd(Args a) {
;     ...
;         for (int i = 0; i < CH_L; ++i) { const u32x2 q = pab[(size_t)i * (LW / 2)];
;             const f32x2 av = (f32x2){__builtin_amdgcn_exp2f(bf_lo(q.x)), __builtin_amdgcn_exp2f(bf_lo(q.y))}, bv = (f32x2){bf_hi(q.x), bf_hi(q.y)}; P = P * av; H = av * H + bv; }
	v_rcp_f32_e32 v15, v15
	v_lshlrev_b32_e32 v24, 16, v110
	v_and_b32_e32 v25, 0xffff0000, v110
	v_pk_mul_f32 v[16:17], v[16:17], v[26:27]
	v_pk_mul_f32 v[12:13], v[88:89], v[12:13]
	v_lshlrev_b32_e32 v32, 16, v111
	v_and_b32_e32 v33, 0xffff0000, v111
	v_pk_mul_f32 v[18:19], v[18:19], v[30:31]
	v_pk_mul_f32 v[16:17], v[16:17], v[24:25]
	v_pk_add_f32 v[8:9], v[8:9], v[92:93]
	v_pk_mul_f32 v[14:15], v[90:91], v[14:15]
	v_pk_mul_f32 v[12:13], v[12:13], s[62:63] op_sel_hi:[1,0]
	v_pk_mul_f32 v[18:19], v[18:19], v[32:33]
	v_cvt_pk_bf16_f32 v16, v20, v16
	v_cvt_pk_bf16_f32 v17, v21, v17
	v_pk_add_f32 v[10:11], v[10:11], v[94:95]
	v_mul_f32_e32 v8, 0xbfb8aa3b, v8
	v_mul_f32_e32 v9, 0xbfb8aa3b, v9
	v_pk_mul_f32 v[14:15], v[14:15], s[62:63] op_sel_hi:[1,0]
	v_exp_f32_e32 v20, v12
	v_exp_f32_e32 v21, v13
	v_cvt_pk_bf16_f32 v18, v22, v18
	v_cvt_pk_bf16_f32 v19, v23, v19
	v_exp_f32_e32 v8, v8
	v_exp_f32_e32 v9, v9
	v_mul_f32_e32 v10, 0xbfb8aa3b, v10
	v_mul_f32_e32 v11, 0xbfb8aa3b, v11
	v_exp_f32_e32 v22, v14
	v_exp_f32_e32 v23, v15
	v_pk_add_f32 v[6:7], v[6:7], v[82:83]
	v_pk_add_f32 v[4:5], v[4:5], v[80:81]
	v_exp_f32_e32 v10, v10
	v_exp_f32_e32 v11, v11
	v_mul_f32_e32 v4, 0xbfb8aa3b, v4
	v_mul_f32_e32 v5, 0xbfb8aa3b, v5
	v_mul_f32_e32 v6, 0xbfb8aa3b, v6
	v_mul_f32_e32 v7, 0xbfb8aa3b, v7
	v_exp_f32_e32 v4, v4
	v_exp_f32_e32 v5, v5
	v_exp_f32_e32 v6, v6
	v_exp_f32_e32 v7, v7
	v_pk_mul_f32 v[20:21], v[20:21], v[20:21]
	v_add_f32_e32 v8, 1.0, v8
	v_add_f32_e32 v9, 1.0, v9
	v_pk_mul_f32 v[22:23], v[22:23], v[22:23]
	v_sub_f32_e32 v20, 1.0, v20
	v_sub_f32_e32 v21, 1.0, v21
	v_rcp_f32_e32 v8, v8
	v_rcp_f32_e32 v9, v9
	v_add_f32_e32 v10, 1.0, v10
	v_add_f32_e32 v11, 1.0, v11
	v_sqrt_f32_e32 v20, v20
	v_sub_f32_e32 v22, 1.0, v22
	v_sub_f32_e32 v23, 1.0, v23
	v_sqrt_f32_e32 v21, v21
	v_rcp_f32_e32 v10, v10
	v_rcp_f32_e32 v11, v11
	v_sqrt_f32_e32 v22, v22
	v_sqrt_f32_e32 v23, v23
	v_add_f32_e32 v4, 1.0, v4
	v_add_f32_e32 v5, 1.0, v5
	v_add_f32_e32 v6, 1.0, v6
	v_add_f32_e32 v7, 1.0, v7
	v_rcp_f32_e32 v4, v4
	v_rcp_f32_e32 v5, v5
	v_rcp_f32_e32 v6, v6
	v_rcp_f32_e32 v7, v7
	global_store_dwordx4 v[28:29], v[16:19], off offset:16
	v_lshlrev_b32_e32 v221, 16, v16
	v_lshlrev_b32_e32 v222, 16, v17
	v_lshlrev_b32_e32 v223, 16, v18
	v_lshlrev_b32_e32 v224, 16, v19
	v_and_b32_e32 v225, 0xffff0000, v16
	v_and_b32_e32 v226, 0xffff0000, v17
	v_and_b32_e32 v227, 0xffff0000, v18
	v_and_b32_e32 v228, 0xffff0000, v19
	v_exp_f32_e32 v221, v221
	v_exp_f32_e32 v222, v222
	v_exp_f32_e32 v223, v223
	v_exp_f32_e32 v224, v224
	v_fmac_f32_dpp v225, v225, v221 row_shr:1 row_mask:0xf bank_mask:0xf
	v_fmac_f32_dpp v226, v226, v222 row_shr:1 row_mask:0xf bank_mask:0xf
	v_fmac_f32_dpp v227, v227, v223 row_shr:1 row_mask:0xf bank_mask:0xf
	v_fmac_f32_dpp v228, v228, v224 row_shr:1 row_mask:0xf bank_mask:0xf
	v_mul_f32_dpp v221, v221, v221 row_shr:1 row_mask:0xf bank_mask:0xf
	v_mul_f32_dpp v222, v222, v222 row_shr:1 row_mask:0xf bank_mask:0xf
	v_mul_f32_dpp v223, v223, v223 row_shr:1 row_mask:0xf bank_mask:0xf
	v_mul_f32_dpp v224, v224, v224 row_shr:1 row_mask:0xf bank_mask:0xf
	v_fmac_f32_dpp v225, v225, v221 row_shr:2 row_mask:0xf bank_mask:0xf
	v_fmac_f32_dpp v226, v226, v222 row_shr:2 row_mask:0xf bank_mask:0xf
	v_fmac_f32_dpp v227, v227, v223 row_shr:2 row_mask:0xf bank_mask:0xf
	v_fmac_f32_dpp v228, v228, v224 row_shr:2 row_mask:0xf bank_mask:0xf
	v_mul_f32_dpp v221, v221, v221 row_shr:2 row_mask:0xf bank_mask:0xf
	v_mul_f32_dpp v222, v222, v222 row_shr:2 row_mask:0xf bank_mask:0xf
	v_mul_f32_dpp v223, v223, v223 row_shr:2 row_mask:0xf bank_mask:0xf
	v_mul_f32_dpp v224, v224, v224 row_shr:2 row_mask:0xf bank_mask:0xf
	v_fmac_f32_dpp v225, v225, v221 row_shr:4 row_mask:0xf bank_mask:0xf
	v_fmac_f32_dpp v226, v226, v222 row_shr:4 row_mask:0xf bank_mask:0xf
	v_fmac_f32_dpp v227, v227, v223 row_shr:4 row_mask:0xf bank_mask:0xf
	v_fmac_f32_dpp v228, v228, v224 row_shr:4 row_mask:0xf bank_mask:0xf
	v_mul_f32_dpp v221, v221, v221 row_shr:4 row_mask:0xf bank_mask:0xf
	v_mul_f32_dpp v222, v222, v222 row_shr:4 row_mask:0xf bank_mask:0xf
	v_mul_f32_dpp v223, v223, v223 row_shr:4 row_mask:0xf bank_mask:0xf
	v_mul_f32_dpp v224, v224, v224 row_shr:4 row_mask:0xf bank_mask:0xf
	v_fmac_f32_dpp v225, v225, v221 row_shr:8 row_mask:0xf bank_mask:0xf
	v_fmac_f32_dpp v226, v226, v222 row_shr:8 row_mask:0xf bank_mask:0xf
	v_fmac_f32_dpp v227, v227, v223 row_shr:8 row_mask:0xf bank_mask:0xf
	v_fmac_f32_dpp v228, v228, v224 row_shr:8 row_mask:0xf bank_mask:0xf
	v_mul_f32_dpp v221, v221, v221 row_shr:8 row_mask:0xf bank_mask:0xf
	v_mul_f32_dpp v222, v222, v222 row_shr:8 row_mask:0xf bank_mask:0xf
	v_mul_f32_dpp v223, v223, v223 row_shr:8 row_mask:0xf bank_mask:0xf
	v_mul_f32_dpp v224, v224, v224 row_shr:8 row_mask:0xf bank_mask:0xf
	v_fma_f32 v242, v242, v221, v225
	v_fma_f32 v243, v243, v222, v226
	v_fma_f32 v244, v244, v223, v227
	v_fma_f32 v245, v245, v224, v228
	v_mul_f32_e32 v238, v238, v221
	v_mul_f32_e32 v239, v239, v222
	v_mul_f32_e32 v240, v240, v223
	v_mul_f32_e32 v241, v241, v224
	v_pk_mul_f32 v[8:9], v[8:9], v[20:21]
	v_lshlrev_b32_e32 v24, 16, v69
	v_lshlrev_b32_e32 v18, 16, v68
	v_and_b32_e32 v19, 0xffff0000, v68
	v_lshlrev_b64 v[16:17], 13, v[198:199]
	v_and_b32_e32 v25, 0xffff0000, v69
	v_pk_mul_f32 v[10:11], v[10:11], v[22:23]
	v_pk_mul_f32 v[8:9], v[8:9], v[18:19]
	v_pk_mul_f32 v[10:11], v[10:11], v[24:25]
	v_cvt_pk_bf16_f32 v8, v12, v8
	v_cvt_pk_bf16_f32 v9, v13, v9
	v_lshl_add_u64 v[12:13], s[92:93], 0, v[16:17]
	v_pk_mul_f32 v[6:7], v[66:67], v[6:7]
	v_pk_mul_f32 v[4:5], v[64:65], v[4:5]
	v_cvt_pk_bf16_f32 v10, v14, v10
	v_cvt_pk_bf16_f32 v11, v15, v11
	v_lshl_add_u64 v[12:13], v[12:13], 0, v[196:197]
; __device__ __forceinline__ unsigned cvt_pk_bf16(float lo, float hi) { unsigned r; asm volatile("v_cvt_pk_bf16_f32 %0, %1, %2" : "=v"(r) : "v"(lo), "v"(hi)); return r; }
; __device__ __forceinline__ float bf_lo(unsigned w) { return __uint_as_float(w << 16); }
; __device__ __forceinline__ float bf_hi(unsigned w) { return __uint_as_float(w & 0xffff0000u); }
;     __device__ __forceinline__ void operator()(EPI_ARGS) const {
;     ...
;                     const f32x4 r = sigmoid4(acc[ai][0][m][n] + ba[n]), ig = sigmoid4(acc[ai][1][m][n] + bi[n]);
;                     const f32x4 la = sp[n] * r * (-1.4426950409f);
;                     f32x4 av;
; #pragma unroll
;                     for (int j = 0; j < 4; ++j) av[j] = __builtin_amdgcn_exp2f(la[j]);
;                     const f32x4 om = 1.0f - av * av; f32x4 sq;
; #pragma unroll
;                     for (int j = 0; j < 4; ++j) sq[j] = __builtin_amdgcn_sqrtf(om[j]);
;                     const f32x4 bx = sq * ig * vx;
;                     u32x4 w; w.x = cvt_pk_bf16(la[0], bx[0]); w.y = cvt_pk_bf16(la[1], bx[1]); w.z = cvt_pk_bf16(la[2], bx[2]); w.w = cvt_pk_bf16(la[3], bx[3]);
;                     *(u32x4*)(AB + (size_t)row * LW + c0 + 4 * n) = w;
; __global__ void __launch_bounds__(NTHR, 2) hybrid_block_fwd(Args a) {
;     ...
;         for (int i = 0; i < CH_L; ++i) { const u32x2 q = pab[(size_t)i * (LW / 2)];
;             const f32x2 av = (f32x2){__builtin_amdgcn_exp2f(bf_lo(q.x)), __builtin_amdgcn_exp2f(bf_lo(q.y))}, bv = (f32x2){bf_hi(q.x), bf_hi(q.y)}; P = P * av; H = av * H + bv; }
	v_pk_add_f32 v[2:3], v[2:3], v[74:75]
	v_pk_add_f32 v[0:1], v[0:1], v[72:73]
	v_pk_mul_f32 v[6:7], v[6:7], s[62:63] op_sel_hi:[1,0]
	v_pk_mul_f32 v[4:5], v[4:5], s[62:63] op_sel_hi:[1,0]
	global_store_dwordx4 v[12:13], v[8:11], off
	v_lshlrev_b32_e32 v221, 16, v8
	v_lshlrev_b32_e32 v222, 16, v9
	v_lshlrev_b32_e32 v223, 16, v10
	v_lshlrev_b32_e32 v224, 16, v11
	v_and_b32_e32 v225, 0xffff0000, v8
	v_and_b32_e32 v226, 0xffff0000, v9
	v_and_b32_e32 v227, 0xffff0000, v10
	v_and_b32_e32 v228, 0xffff0000, v11
	v_exp_f32_e32 v221, v221
	v_exp_f32_e32 v222, v222
	v_exp_f32_e32 v223, v223
	v_exp_f32_e32 v224, v224
	v_fmac_f32_dpp v225, v225, v221 row_shr:1 row_mask:0xf bank_mask:0xf
	v_fmac_f32_dpp v226, v226, v222 row_shr:1 row_mask:0xf bank_mask:0xf
	v_fmac_f32_dpp v227, v227, v223 row_shr:1 row_mask:0xf bank_mask:0xf
	v_fmac_f32_dpp v228, v228, v224 row_shr:1 row_mask:0xf bank_mask:0xf
	v_mul_f32_dpp v221, v221, v221 row_shr:1 row_mask:0xf bank_mask:0xf
	v_mul_f32_dpp v222, v222, v222 row_shr:1 row_mask:0xf bank_mask:0xf
	v_mul_f32_dpp v223, v223, v223 row_shr:1 row_mask:0xf bank_mask:0xf
	v_mul_f32_dpp v224, v224, v224 row_shr:1 row_mask:0xf bank_mask:0xf
	v_fmac_f32_dpp v225, v225, v221 row_shr:2 row_mask:0xf bank_mask:0xf
	v_fmac_f32_dpp v226, v226, v222 row_shr:2 row_mask:0xf bank_mask:0xf
	v_fmac_f32_dpp v227, v227, v223 row_shr:2 row_mask:0xf bank_mask:0xf
	v_fmac_f32_dpp v228, v228, v224 row_shr:2 row_mask:0xf bank_mask:0xf
	v_mul_f32_dpp v221, v221, v221 row_shr:2 row_mask:0xf bank_mask:0xf
	v_mul_f32_dpp v222, v222, v222 row_shr:2 row_mask:0xf bank_mask:0xf
	v_mul_f32_dpp v223, v223, v223 row_shr:2 row_mask:0xf bank_mask:0xf
	v_mul_f32_dpp v224, v224, v224 row_shr:2 row_mask:0xf bank_mask:0xf
	v_fmac_f32_dpp v225, v225, v221 row_shr:4 row_mask:0xf bank_mask:0xf
	v_fmac_f32_dpp v226, v226, v222 row_shr:4 row_mask:0xf bank_mask:0xf
	v_fmac_f32_dpp v227, v227, v223 row_shr:4 row_mask:0xf bank_mask:0xf
	v_fmac_f32_dpp v228, v228, v224 row_shr:4 row_mask:0xf bank_mask:0xf
	v_mul_f32_dpp v221, v221, v221 row_shr:4 row_mask:0xf bank_mask:0xf
	v_mul_f32_dpp v222, v222, v222 row_shr:4 row_mask:0xf bank_mask:0xf
	v_mul_f32_dpp v223, v223, v223 row_shr:4 row_mask:0xf bank_mask:0xf
	v_mul_f32_dpp v224, v224, v224 row_shr:4 row_mask:0xf bank_mask:0xf
	v_fmac_f32_dpp v225, v225, v221 row_shr:8 row_mask:0xf bank_mask:0xf
	v_fmac_f32_dpp v226, v226, v222 row_shr:8 row_mask:0xf bank_mask:0xf
	v_fmac_f32_dpp v227, v227, v223 row_shr:8 row_mask:0xf bank_mask:0xf
	v_fmac_f32_dpp v228, v228, v224 row_shr:8 row_mask:0xf bank_mask:0xf
	v_mul_f32_dpp v221, v221, v221 row_shr:8 row_mask:0xf bank_mask:0xf
	v_mul_f32_dpp v222, v222, v222 row_shr:8 row_mask:0xf bank_mask:0xf
	v_mul_f32_dpp v223, v223, v223 row_shr:8 row_mask:0xf bank_mask:0xf
	v_mul_f32_dpp v224, v224, v224 row_shr:8 row_mask:0xf bank_mask:0xf
	v_fma_f32 v234, v234, v221, v225
	v_fma_f32 v235, v235, v222, v226
	v_fma_f32 v236, v236, v223, v227
	v_fma_f32 v237, v237, v224, v228
	v_mul_f32_e32 v230, v230, v221
	v_mul_f32_e32 v231, v231, v222
	v_mul_f32_e32 v232, v232, v223
	v_mul_f32_e32 v233, v233, v224
	v_mul_f32_e32 v0, 0xbfb8aa3b, v0
	v_mul_f32_e32 v1, 0xbfb8aa3b, v1
	v_mul_f32_e32 v2, 0xbfb8aa3b, v2
	v_mul_f32_e32 v3, 0xbfb8aa3b, v3
	v_exp_f32_e32 v10, v4
	v_exp_f32_e32 v14, v6
	v_exp_f32_e32 v15, v7
	v_exp_f32_e32 v11, v5
	v_exp_f32_e32 v0, v0
	v_exp_f32_e32 v1, v1
	v_exp_f32_e32 v2, v2
	v_exp_f32_e32 v3, v3
	v_pk_mul_f32 v[14:15], v[14:15], v[14:15]
	v_pk_mul_f32 v[10:11], v[10:11], v[10:11]
	v_add_f32_e32 v0, 1.0, v0
	v_add_f32_e32 v1, 1.0, v1
	v_add_f32_e32 v2, 1.0, v2
	v_add_f32_e32 v3, 1.0, v3
	v_sub_f32_e32 v10, 1.0, v10
	v_sub_f32_e32 v11, 1.0, v11
	v_sub_f32_e32 v14, 1.0, v14
	v_sub_f32_e32 v15, 1.0, v15
	v_rcp_f32_e32 v0, v0
	v_rcp_f32_e32 v1, v1
	v_rcp_f32_e32 v2, v2
	v_rcp_f32_e32 v3, v3
	v_sqrt_f32_e32 v10, v10
	v_sqrt_f32_e32 v14, v14
	v_sqrt_f32_e32 v15, v15
	v_sqrt_f32_e32 v11, v11
	v_lshlrev_b32_e32 v8, 16, v70
	v_and_b32_e32 v9, 0xffff0000, v70
	v_lshlrev_b32_e32 v16, 16, v71
	v_and_b32_e32 v17, 0xffff0000, v71
	v_pk_mul_f32 v[2:3], v[2:3], v[14:15]
	v_pk_mul_f32 v[0:1], v[0:1], v[10:11]
	v_pk_mul_f32 v[2:3], v[2:3], v[16:17]
	v_pk_mul_f32 v[0:1], v[0:1], v[8:9]
	s_nop 0
	v_cvt_pk_bf16_f32 v0, v4, v0
	v_cvt_pk_bf16_f32 v1, v5, v1
	v_cvt_pk_bf16_f32 v2, v6, v2
	v_cvt_pk_bf16_f32 v3, v7, v3
	global_store_dwordx4 v[12:13], v[0:3], off offset:16
	v_lshlrev_b32_e32 v221, 16, v0
	v_lshlrev_b32_e32 v222, 16, v1
	v_lshlrev_b32_e32 v223, 16, v2
	v_lshlrev_b32_e32 v224, 16, v3
	v_and_b32_e32 v225, 0xffff0000, v0
	v_and_b32_e32 v226, 0xffff0000, v1
	v_and_b32_e32 v227, 0xffff0000, v2
	v_and_b32_e32 v228, 0xffff0000, v3
	v_exp_f32_e32 v221, v221
	v_exp_f32_e32 v222, v222
	v_exp_f32_e32 v223, v223
	v_exp_f32_e32 v224, v224
	v_fmac_f32_dpp v225, v225, v221 row_shr:1 row_mask:0xf bank_mask:0xf
	v_fmac_f32_dpp v226, v226, v222 row_shr:1 row_mask:0xf bank_mask:0xf
	v_fmac_f32_dpp v227, v227, v223 row_shr:1 row_mask:0xf bank_mask:0xf
	v_fmac_f32_dpp v228, v228, v224 row_shr:1 row_mask:0xf bank_mask:0xf
	v_mul_f32_dpp v221, v221, v221 row_shr:1 row_mask:0xf bank_mask:0xf
	v_mul_f32_dpp v222, v222, v222 row_shr:1 row_mask:0xf bank_mask:0xf
; __device__ __forceinline__ float bf_lo(unsigned w) { return __uint_as_float(w << 16); }
; __device__ __forceinline__ float bf_hi(unsigned w) { return __uint_as_float(w & 0xffff0000u); }
; __global__ void __launch_bounds__(NTHR, 2) hybrid_block_fwd(Args a) {
;     ...
;         for (int i = 0; i < CH_L; ++i) { const u32x2 q = pab[(size_t)i * (LW / 2)];
;             const f32x2 av = (f32x2){__builtin_amdgcn_exp2f(bf_lo(q.x)), __builtin_amdgcn_exp2f(bf_lo(q.y))}, bv = (f32x2){bf_hi(q.x), bf_hi(q.y)}; P = P * av; H = av * H + bv; }
;         ((f32x2*)(AGGP + (size_t)(b * NCH + chunk) * LW))[c2] = P; ((f32x2*)(AGGH + (size_t)(b * NCH + chunk) * LW))[c2] = H;
	v_mul_f32_dpp v223, v223, v223 row_shr:1 row_mask:0xf bank_mask:0xf
	v_mul_f32_dpp v224, v224, v224 row_shr:1 row_mask:0xf bank_mask:0xf
	v_fmac_f32_dpp v225, v225, v221 row_shr:2 row_mask:0xf bank_mask:0xf
	v_fmac_f32_dpp v226, v226, v222 row_shr:2 row_mask:0xf bank_mask:0xf
	v_fmac_f32_dpp v227, v227, v223 row_shr:2 row_mask:0xf bank_mask:0xf
	v_fmac_f32_dpp v228, v228, v224 row_shr:2 row_mask:0xf bank_mask:0xf
	v_mul_f32_dpp v221, v221, v221 row_shr:2 row_mask:0xf bank_mask:0xf
	v_mul_f32_dpp v222, v222, v222 row_shr:2 row_mask:0xf bank_mask:0xf
	v_mul_f32_dpp v223, v223, v223 row_shr:2 row_mask:0xf bank_mask:0xf
	v_mul_f32_dpp v224, v224, v224 row_shr:2 row_mask:0xf bank_mask:0xf
	v_fmac_f32_dpp v225, v225, v221 row_shr:4 row_mask:0xf bank_mask:0xf
	v_fmac_f32_dpp v226, v226, v222 row_shr:4 row_mask:0xf bank_mask:0xf
	v_fmac_f32_dpp v227, v227, v223 row_shr:4 row_mask:0xf bank_mask:0xf
	v_fmac_f32_dpp v228, v228, v224 row_shr:4 row_mask:0xf bank_mask:0xf
	v_mul_f32_dpp v221, v221, v221 row_shr:4 row_mask:0xf bank_mask:0xf
	v_mul_f32_dpp v222, v222, v222 row_shr:4 row_mask:0xf bank_mask:0xf
	v_mul_f32_dpp v223, v223, v223 row_shr:4 row_mask:0xf bank_mask:0xf
	v_mul_f32_dpp v224, v224, v224 row_shr:4 row_mask:0xf bank_mask:0xf
	v_fmac_f32_dpp v225, v225, v221 row_shr:8 row_mask:0xf bank_mask:0xf
	v_fmac_f32_dpp v226, v226, v222 row_shr:8 row_mask:0xf bank_mask:0xf
	v_fmac_f32_dpp v227, v227, v223 row_shr:8 row_mask:0xf bank_mask:0xf
	v_fmac_f32_dpp v228, v228, v224 row_shr:8 row_mask:0xf bank_mask:0xf
	v_mul_f32_dpp v221, v221, v221 row_shr:8 row_mask:0xf bank_mask:0xf
	v_mul_f32_dpp v222, v222, v222 row_shr:8 row_mask:0xf bank_mask:0xf
	v_mul_f32_dpp v223, v223, v223 row_shr:8 row_mask:0xf bank_mask:0xf
	v_mul_f32_dpp v224, v224, v224 row_shr:8 row_mask:0xf bank_mask:0xf
	v_fma_f32 v242, v242, v221, v225
	v_fma_f32 v243, v243, v222, v226
	v_fma_f32 v244, v244, v223, v227
	v_fma_f32 v245, v245, v224, v228
	v_mul_f32_e32 v238, v238, v221
	v_mul_f32_e32 v239, v239, v222
	v_mul_f32_e32 v240, v240, v223
	v_mul_f32_e32 v241, v241, v224
	s_mov_b64 s[4:5], vcc
	v_and_b32_e32 v1, 15, v212
	v_lshrrev_b32_e32 v2, 4, v212
	v_and_b32_e32 v2, 15, v2
	v_readfirstlane_b32 s22, v212
	v_lshlrev_b32_e32 v3, 6, v2
	v_add_u32_e32 v3, 0x20400, v3
	v_cmp_eq_u32_e32 vcc, 15, v1
	s_lshr_b32 s22, s22, 8
	s_cmp_lg_u32 s22, 0
	s_cbranch_scc1 .Lagg_wr1
	s_and_saveexec_b64 s[22:23], vcc
	ds_write_b128 v3, v[152:155]
	ds_write_b128 v3, v[156:159] offset:16
	ds_write_b128 v3, v[160:163] offset:32
	ds_write_b128 v3, v[164:167] offset:48
	ds_write_b128 v3, v[230:233] offset:1024
	ds_write_b128 v3, v[234:237] offset:1040
	ds_write_b128 v3, v[238:241] offset:1056
	ds_write_b128 v3, v[242:245] offset:1072
	s_or_b64 exec, exec, s[22:23]
	s_waitcnt lgkmcnt(0)
	s_barrier
	s_branch .Lagg_done
.Lagg_wr1:
	s_barrier
	s_and_saveexec_b64 s[22:23], vcc
	ds_read_b128 v[112:115], v3
	ds_read_b128 v[116:119], v3 offset:16
	ds_read_b128 v[120:123], v3 offset:32
	ds_read_b128 v[124:127], v3 offset:48
	ds_read_b128 v[132:135], v3 offset:1024
	ds_read_b128 v[136:139], v3 offset:1040
	ds_read_b128 v[140:143], v3 offset:1056
	ds_read_b128 v[144:147], v3 offset:1072
	s_lshl_b32 s32, s74, 12
	s_lshl_b32 s45, s27, 7
	s_add_u32 s78, s94, 0x100000
	s_addc_u32 s79, s95, 0
	s_add_i32 s32, s32, s45
	v_lshl_add_u32 v4, v2, 3, s32
	v_lshlrev_b32_e32 v4, 2, v4
	v_add_u32_e32 v5, 0x2000, v4
	v_add_u32_e32 v6, 0x100000, v4
	v_add_u32_e32 v7, 0x102000, v4
	s_waitcnt lgkmcnt(0)
	v_fmac_f32_e32 v156, v116, v152
	v_fmac_f32_e32 v157, v117, v153
	v_fmac_f32_e32 v158, v118, v154
	v_fmac_f32_e32 v159, v119, v155
	v_mul_f32_e32 v152, v112, v152
	v_mul_f32_e32 v153, v113, v153
	v_mul_f32_e32 v154, v114, v154
	v_mul_f32_e32 v155, v115, v155
	v_fmac_f32_e32 v164, v124, v160
	v_fmac_f32_e32 v165, v125, v161
	v_fmac_f32_e32 v166, v126, v162
	v_fmac_f32_e32 v167, v127, v163
	v_mul_f32_e32 v160, v120, v160
	v_mul_f32_e32 v161, v121, v161
	v_mul_f32_e32 v162, v122, v162
	v_mul_f32_e32 v163, v123, v163
	v_fmac_f32_e32 v234, v136, v230
	v_fmac_f32_e32 v235, v137, v231
	v_fmac_f32_e32 v236, v138, v232
	v_fmac_f32_e32 v237, v139, v233
	v_mul_f32_e32 v230, v132, v230
	v_mul_f32_e32 v231, v133, v231
	v_mul_f32_e32 v232, v134, v232
	v_mul_f32_e32 v233, v135, v233
	v_fmac_f32_e32 v242, v144, v238
	v_fmac_f32_e32 v243, v145, v239
	v_fmac_f32_e32 v244, v146, v240
	v_fmac_f32_e32 v245, v147, v241
	v_mul_f32_e32 v238, v140, v238
	v_mul_f32_e32 v239, v141, v239
	v_mul_f32_e32 v240, v142, v240
	v_mul_f32_e32 v241, v143, v241
	global_store_dwordx4 v4, v[152:155], s[78:79]
	global_store_dwordx4 v4, v[160:163], s[78:79] offset:16
	global_store_dwordx4 v5, v[230:233], s[78:79]
	global_store_dwordx4 v5, v[238:241], s[78:79] offset:16
	global_store_dwordx4 v6, v[156:159], s[78:79]
	global_store_dwordx4 v6, v[164:167], s[78:79] offset:16
	global_store_dwordx4 v7, v[234:237], s[78:79]
	global_store_dwordx4 v7, v[242:245], s[78:79] offset:16
	s_or_b64 exec, exec, s[22:23]
.Lagg_done:
	s_mov_b64 vcc, s[4:5]
	s_cbranch_vccnz .LBB0_543
	s_andn2_b64 vcc, exec, s[10:11]
	s_cbranch_vccnz .LBB0_542
	s_barrier
	s_branch .LBB0_542
